# P7 (S5 ygemm) unit order refined: the 4 groups sharing an output cache line and the 4 time-quarters sharing A run together on one XCD
# baseline (speedup 1.0000x reference)
; #define LAS __attribute__((address_space(3)))
; #define MFMA16(a, b, c) __builtin_amdgcn_mfma_f32_16x16x32_bf16((a), (b), (c), 0, 0, 0)
; #define S5Y_LOAD(slot, it) do { rb[slot][0] = *(const u32x4*)(Bsrc + (it) * 64); rb[slot][1] = *(const u32x4*)(Bsrc + (size_t)64 * 768 + (it) * 64); \
;         _Pragma("unroll") for (int ks = 0; ks < 2; ++ks) _Pragma("unroll") for (int m = 0; m < 2; ++m) af[slot][ks * 2 + m] = s5_ya(Ab, Xb, m, 2 * (it) + ks); } while (0)
; #define S5Y_PUT(slot, buf) do { *(LAS u32x4*)(bdst + (buf) * BUFB) = rb[slot][0]; *(LAS u32x4*)(bdst + (buf) * BUFB + 64 * ROWB) = rb[slot][1]; } while (0)
; __device__ __forceinline__ void s5_ygemm(LAS unsigned char* lds, const bf16_t* Z, const bf16_t* W3, const float* E, bf16_t* YG, int unit, int tid) {
;     const int nq = unit & 3, mb3 = (unit >> 2) % 3, g = unit / 12;
;     const int wid = tid >> 6, lane = tid & 63, fr = lane & 15, fq = lane >> 4;
;     const int cbase = mb3 * 256 + wid * 32;
;     f32x4 acc[2][8];
; #pragma unroll
;     for (int m = 0; m < 2; ++m)
; #pragma unroll
;         for (int n = 0; n < 8; ++n) acc[m][n] = (f32x4){0.f, 0.f, 0.f, 0.f};
;     const bf16_t* Ab = Z + ((size_t)(g * S5NCB + (cbase >> 4)) * 32 + (fq >> 1)) * 256 + fr * 16 + (fq & 1) * 8;
;     const bf16_t* Xb = (const bf16_t*)(E + (size_t)(cbase + fr) * 16384 + g * 256) + fq * 8;
;     const bf16_t* Bsrc = W3 + (size_t)g * 512 * 768 + (size_t)(nq * 128 + (tid >> 3)) * 768 + (tid & 7) * 8;
;     constexpr int ROWB = 144, BUFB = 128 * ROWB;
;     LAS unsigned char* bdst = lds + (tid >> 3) * ROWB + (tid & 7) * 16;
;     const LAS unsigned char* brd = lds + fr * ROWB + fq * 16;
;     u32x4 rb[5][2]; bf16x8 af[5][4];
;     ...
;     S5Y_LOAD(0, 0); S5Y_LOAD(1, 1); S5Y_LOAD(2, 2); S5Y_LOAD(3, 3);
;     S5Y_PUT(0, 0);
;     S5Y_BAR();
; #pragma unroll
;     for (int it = 0; it < 12; ++it) {
;         if (it + 4 < 12) S5Y_LOAD((it + 4) % 5, it + 4);
;         const LAS unsigned char* rbuf = brd + (it & 1) * BUFB;
; #pragma unroll
;         for (int ks = 0; ks < 2; ++ks)
; #pragma unroll
;             for (int n = 0; n < 8; ++n) { const bf16x8 bf = *(const LAS bf16x8*)(rbuf + n * 16 * ROWB + ks * 64);
; #pragma unroll
;                 for (int m = 0; m < 2; ++m) acc[m][n] = MFMA16(bf, af[it % 5][ks * 2 + m], acc[m][n]); }
.LBB0_755:
	s_lshr_b32 s60, s18, 4
	s_mul_i32 s61, s60, 43
	s_lshr_b32 s61, s61, 7
	s_mul_i32 s62, s61, 3
	s_sub_i32 s60, s60, s62
	s_lshl_b32 s61, s61, 2
	s_and_b32 s62, s18, 3
	s_add_i32 s61, s61, s62
	s_mul_i32 s61, s61, 12
	s_lshl_b32 s60, s60, 2
	s_add_i32 s60, s60, s61
	s_lshr_b32 s62, s18, 2
	s_and_b32 s62, s62, 3
	s_add_i32 s60, s60, s62
	s_cmp_eq_u32 s76, 0x100
	s_cselect_b32 s60, s60, s18
	s_ashr_i32 s21, s60, 2
	s_mul_hi_i32 s4, s60, 0x2aaaaaab
	s_lshr_b32 s5, s4, 31
	s_ashr_i32 s20, s4, 1
	s_mul_hi_i32 s4, s21, 0x55555556
	s_add_i32 s20, s20, s5
	s_lshr_b32 s5, s4, 31
	s_add_i32 s5, s4, s5
	s_lshl_b32 s4, s20, 8
	s_mul_i32 s24, s5, 3
	s_and_b32 s19, s60, 3
	s_mul_i32 s22, s20, 0xc0000
	s_ashr_i32 s5, s4, 31
	s_sub_i32 s21, s21, s24
	s_mul_hi_i32 s23, s20, 0xc0000
	s_add_u32 s22, s2, s22
	v_lshl_add_u32 v114, s21, 8, v142
	s_addc_u32 s23, s8, s23
	v_lshl_add_u32 v4, s19, 7, v144
	v_ashrrev_i32_e32 v0, 4, v114
	v_mov_b64_e32 v[2:3], s[22:23]
	v_mad_u64_u32 v[0:1], s[24:25], s20, 48, v[0:1]
	v_mad_i64_i32 v[2:3], s[22:23], v4, s6, v[2:3]
	v_ashrrev_i32_e32 v1, 31, v0
	v_lshl_add_u64 v[134:135], v[2:3], 0, v[130:131]
	v_lshlrev_b64 v[0:1], 14, v[0:1]
	v_add_co_u32_e32 v136, vcc, s7, v134
	v_lshl_add_u64 v[52:53], v[126:127], 0, v[0:1]
	s_nop 0
	v_addc_co_u32_e32 v137, vcc, 0, v135, vcc
	global_load_dwordx4 v[0:3], v[134:135], off
	global_load_dwordx4 v[4:7], v[134:135], off offset:128
	global_load_dwordx4 v[48:51], v[134:135], off offset:256
	global_load_dwordx4 v[56:59], v[134:135], off offset:384
	global_load_dwordx4 v[8:11], v[136:137], off
	v_add_co_u32_e32 v54, vcc, s9, v52
	global_load_dwordx4 v[12:15], v[52:53], off
	global_load_dwordx4 v[36:39], v[52:53], off offset:1024
	global_load_dwordx4 v[44:47], v[136:137], off offset:128
	global_load_dwordx4 v[80:83], v[52:53], off offset:2048
	global_load_dwordx4 v[88:91], v[52:53], off offset:3072
	v_addc_co_u32_e32 v55, vcc, 0, v53, vcc
	v_add_co_u32_e32 v64, vcc, s11, v52
	s_lshl_b32 s19, s19, 3
	s_nop 0
	v_addc_co_u32_e32 v65, vcc, 0, v53, vcc
	v_add_co_u32_e32 v66, vcc, s10, v52
	s_add_i32 s18, s18, s76
	s_nop 0
	v_addc_co_u32_e32 v67, vcc, 0, v53, vcc
	v_add_co_u32_e32 v132, vcc, s12, v52
	s_nop 1
	v_addc_co_u32_e32 v133, vcc, 0, v53, vcc
	global_load_dwordx4 v[92:95], v[136:137], off offset:256
	global_load_dwordx4 v[68:71], v[136:137], off offset:384
	global_load_dwordx4 v[60:63], v[64:65], off offset:-4096
	global_load_dwordx4 v[84:87], v[54:55], off offset:1024
	global_load_dwordx4 v[96:99], v[54:55], off offset:2048
	global_load_dwordx4 v[20:23], v[64:65], off
	global_load_dwordx4 v[100:103], v[54:55], off offset:3072
	global_load_dwordx4 v[76:79], v[66:67], off offset:1024
	global_load_dwordx4 v[72:75], v[64:65], off offset:1024
	global_load_dwordx4 v[32:35], v[64:65], off offset:2048
	global_load_dwordx4 v[40:43], v[66:67], off offset:2048
	global_load_dwordx4 v[24:27], v[66:67], off offset:3072
	global_load_dwordx4 v[28:31], v[132:133], off offset:-4096
	global_load_dwordx4 v[16:19], v[64:65], off offset:3072
	v_add_co_u32_e32 v54, vcc, s13, v52
	s_waitcnt vmcnt(23)
	ds_write_b128 v146, v[0:3]
	s_waitcnt vmcnt(19)
	ds_write_b128 v146, v[8:11] offset:9216
	s_waitcnt lgkmcnt(0)
	s_barrier
	ds_read_b128 v[0:3], v145
	ds_read_b128 v[8:11], v145 offset:64
	ds_read_b128 v[104:107], v145 offset:2304
	ds_read_b128 v[108:111], v145 offset:2368
	ds_read_b128 v[120:123], v145 offset:4608
	ds_read_b128 v[138:141], v145 offset:4672
	ds_read_b128 v[152:155], v145 offset:6912
	ds_read_b128 v[156:159], v145 offset:6976
	ds_read_b128 v[168:171], v145 offset:9216
	ds_read_b128 v[172:175], v145 offset:9280
	ds_read_b128 v[180:183], v145 offset:11520
	ds_read_b128 v[184:187], v145 offset:11584
	ds_read_b128 v[192:195], v145 offset:13824
	ds_read_b128 v[196:199], v145 offset:13888
	ds_read_b128 v[204:207], v145 offset:16128
	ds_read_b128 v[208:211], v145 offset:16192
	s_waitcnt vmcnt(18) lgkmcnt(14)
	v_mfma_f32_16x16x32_bf16 v[64:67], v[0:3], v[12:15], 0
	v_addc_co_u32_e32 v55, vcc, 0, v53, vcc
	v_add_co_u32_e32 v112, vcc, s15, v52
	s_waitcnt vmcnt(11)
	v_mfma_f32_16x16x32_bf16 v[0:3], v[0:3], v[60:63], 0
	v_addc_co_u32_e32 v113, vcc, 0, v53, vcc
	s_waitcnt lgkmcnt(13)
	v_mfma_f32_16x16x32_bf16 v[116:119], v[104:107], v[12:15], 0
	v_mfma_f32_16x16x32_bf16 v[104:107], v[104:107], v[60:63], 0
	s_waitcnt lgkmcnt(11)
	v_mfma_f32_16x16x32_bf16 v[148:151], v[120:123], v[12:15], 0
	v_mfma_f32_16x16x32_bf16 v[120:123], v[120:123], v[60:63], 0
	s_waitcnt lgkmcnt(9)
	v_mfma_f32_16x16x32_bf16 v[160:163], v[152:155], v[12:15], 0
	v_mfma_f32_16x16x32_bf16 v[152:155], v[152:155], v[60:63], 0
	s_waitcnt lgkmcnt(7)
	v_mfma_f32_16x16x32_bf16 v[176:179], v[168:171], v[12:15], 0
	v_mfma_f32_16x16x32_bf16 v[168:171], v[168:171], v[60:63], 0
	s_waitcnt lgkmcnt(5)
	v_mfma_f32_16x16x32_bf16 v[188:191], v[180:183], v[12:15], 0
	v_mfma_f32_16x16x32_bf16 v[180:183], v[180:183], v[60:63], 0
	s_waitcnt lgkmcnt(3)
	v_mfma_f32_16x16x32_bf16 v[200:203], v[192:195], v[12:15], 0
	v_mfma_f32_16x16x32_bf16 v[192:195], v[192:195], v[60:63], 0
	s_waitcnt lgkmcnt(1)
	v_mfma_f32_16x16x32_bf16 v[12:15], v[204:207], v[12:15], 0
	v_mfma_f32_16x16x32_bf16 v[204:207], v[204:207], v[60:63], 0
	v_mfma_f32_16x16x32_bf16 v[212:215], v[8:11], v[36:39], v[64:67]
	s_waitcnt vmcnt(10)
	v_mfma_f32_16x16x32_bf16 v[216:219], v[8:11], v[84:87], v[0:3]
	v_mfma_f32_16x16x32_bf16 v[116:119], v[108:111], v[36:39], v[116:119]
	v_mfma_f32_16x16x32_bf16 v[220:223], v[108:111], v[84:87], v[104:107]
	s_nop 2
	global_load_dwordx4 v[104:107], v[134:135], off offset:512
	global_load_dwordx4 v[108:111], v[136:137], off offset:512
	global_load_dwordx4 v[60:63], v[132:133], off
	global_load_dwordx4 v[64:67], v[112:113], off offset:-4096
	global_load_dwordx4 v[8:11], v[132:133], off offset:1024
	global_load_dwordx4 v[0:3], v[54:55], off offset:1024
	ds_write_b128 v146, v[4:7] offset:18432
	ds_write_b128 v146, v[44:47] offset:27648
	s_waitcnt lgkmcnt(0)
	s_barrier
; #define LAS __attribute__((address_space(3)))
; #define MFMA16(a, b, c) __builtin_amdgcn_mfma_f32_16x16x32_bf16((a), (b), (c), 0, 0, 0)
; #define S5Y_LOAD(slot, it) do { rb[slot][0] = *(const u32x4*)(Bsrc + (it) * 64); rb[slot][1] = *(const u32x4*)(Bsrc + (size_t)64 * 768 + (it) * 64); \
;         _Pragma("unroll") for (int ks = 0; ks < 2; ++ks) _Pragma("unroll") for (int m = 0; m < 2; ++m) af[slot][ks * 2 + m] = s5_ya(Ab, Xb, m, 2 * (it) + ks); } while (0)
; #define S5Y_PUT(slot, buf) do { *(LAS u32x4*)(bdst + (buf) * BUFB) = rb[slot][0]; *(LAS u32x4*)(bdst + (buf) * BUFB + 64 * ROWB) = rb[slot][1]; } while (0)
; #define S5Y_BAR() do { asm volatile("s_waitcnt lgkmcnt(0)" ::: "memory"); __builtin_amdgcn_s_barrier(); asm volatile("" ::: "memory"); } while (0)
; __device__ __forceinline__ void s5_ygemm(LAS unsigned char* lds, const bf16_t* Z, const bf16_t* W3, const float* E, bf16_t* YG, int unit, int tid) {
;     ...
; #pragma unroll
;     for (int it = 0; it < 12; ++it) {
;         if (it + 4 < 12) S5Y_LOAD((it + 4) % 5, it + 4);
;         const LAS unsigned char* rbuf = brd + (it & 1) * BUFB;
; #pragma unroll
;         for (int ks = 0; ks < 2; ++ks)
; #pragma unroll
;             for (int n = 0; n < 8; ++n) { const bf16x8 bf = *(const LAS bf16x8*)(rbuf + n * 16 * ROWB + ks * 64);
; #pragma unroll
;                 for (int m = 0; m < 2; ++m) acc[m][n] = MFMA16(bf, af[it % 5][ks * 2 + m], acc[m][n]); }
;         if (it + 1 < 12) S5Y_PUT((it + 1) % 5, (it + 1) & 1);
;         S5Y_BAR();
;     }
	v_mfma_f32_16x16x32_bf16 v[148:151], v[138:141], v[36:39], v[148:151]
	v_mfma_f32_16x16x32_bf16 v[120:123], v[138:141], v[84:87], v[120:123]
	v_mfma_f32_16x16x32_bf16 v[138:141], v[156:159], v[36:39], v[160:163]
	v_mfma_f32_16x16x32_bf16 v[152:155], v[156:159], v[84:87], v[152:155]
	v_mfma_f32_16x16x32_bf16 v[156:159], v[172:175], v[36:39], v[176:179]
	v_mfma_f32_16x16x32_bf16 v[160:163], v[172:175], v[84:87], v[168:171]
	v_mfma_f32_16x16x32_bf16 v[168:171], v[184:187], v[36:39], v[188:191]
	v_mfma_f32_16x16x32_bf16 v[172:175], v[184:187], v[84:87], v[180:183]
	v_mfma_f32_16x16x32_bf16 v[176:179], v[196:199], v[36:39], v[200:203]
	v_mfma_f32_16x16x32_bf16 v[180:183], v[196:199], v[84:87], v[192:195]
	s_waitcnt lgkmcnt(2)
	v_mfma_f32_16x16x32_bf16 v[4:7], v[208:211], v[36:39], v[12:15]
	ds_read_b128 v[36:39], v145 offset:18432
	ds_read_b128 v[44:47], v145 offset:18496
	ds_read_b128 v[184:187], v145 offset:20736
	ds_read_b128 v[188:191], v145 offset:20800
	ds_read_b128 v[192:195], v145 offset:23040
	ds_read_b128 v[196:199], v145 offset:23104
	s_waitcnt lgkmcnt(1)
	v_mfma_f32_16x16x32_bf16 v[148:151], v[192:195], v[80:83], v[148:151]
	s_waitcnt vmcnt(15)
	v_mfma_f32_16x16x32_bf16 v[120:123], v[192:195], v[96:99], v[120:123]
	ds_read_b128 v[192:195], v145 offset:25344
	ds_read_b128 v[200:203], v145 offset:25408
	v_mfma_f32_16x16x32_bf16 v[12:15], v[208:211], v[84:87], v[204:207]
	s_waitcnt lgkmcnt(1)
	v_mfma_f32_16x16x32_bf16 v[138:141], v[192:195], v[80:83], v[138:141]
	v_mfma_f32_16x16x32_bf16 v[152:155], v[192:195], v[96:99], v[152:155]
	ds_read_b128 v[192:195], v145 offset:27648
	ds_read_b128 v[204:207], v145 offset:27712
	s_waitcnt lgkmcnt(1)
	v_mfma_f32_16x16x32_bf16 v[156:159], v[192:195], v[80:83], v[156:159]
	v_mfma_f32_16x16x32_bf16 v[160:163], v[192:195], v[96:99], v[160:163]
	ds_read_b128 v[192:195], v145 offset:29952
	ds_read_b128 v[208:211], v145 offset:30016
	v_mfma_f32_16x16x32_bf16 v[84:87], v[36:39], v[80:83], v[212:215]
	s_waitcnt lgkmcnt(1)
	v_mfma_f32_16x16x32_bf16 v[168:171], v[192:195], v[80:83], v[168:171]
	v_mfma_f32_16x16x32_bf16 v[172:175], v[192:195], v[96:99], v[172:175]
	ds_read_b128 v[192:195], v145 offset:32256
	ds_read_b128 v[212:215], v145 offset:32320
	v_mfma_f32_16x16x32_bf16 v[36:39], v[36:39], v[96:99], v[216:219]
	s_waitcnt lgkmcnt(1)
	v_mfma_f32_16x16x32_bf16 v[176:179], v[192:195], v[80:83], v[176:179]
	v_mfma_f32_16x16x32_bf16 v[180:183], v[192:195], v[96:99], v[180:183]
	ds_read_b128 v[192:195], v145 offset:34560
	ds_read_b128 v[216:219], v145 offset:34624
	v_mfma_f32_16x16x32_bf16 v[116:119], v[184:187], v[80:83], v[116:119]
	v_mfma_f32_16x16x32_bf16 v[184:187], v[184:187], v[96:99], v[220:223]
	s_waitcnt lgkmcnt(1)
	v_mfma_f32_16x16x32_bf16 v[220:223], v[192:195], v[80:83], v[4:7]
	v_mfma_f32_16x16x32_bf16 v[96:99], v[192:195], v[96:99], v[12:15]
	v_mfma_f32_16x16x32_bf16 v[192:195], v[44:47], v[88:91], v[84:87]
	global_load_dwordx4 v[80:83], v[134:135], off offset:640
	s_nop 1
	global_load_dwordx4 v[84:87], v[136:137], off offset:640
	s_waitcnt vmcnt(15)
	v_mfma_f32_16x16x32_bf16 v[224:227], v[44:47], v[100:103], v[36:39]
	s_nop 2
	global_load_dwordx4 v[36:39], v[54:55], off offset:2048
	global_load_dwordx4 v[44:47], v[132:133], off offset:2048
	global_load_dwordx4 v[12:15], v[132:133], off offset:3072
	global_load_dwordx4 v[4:7], v[54:55], off offset:3072
	ds_write_b128 v146, v[48:51]
	ds_write_b128 v146, v[92:95] offset:9216
	s_waitcnt lgkmcnt(0)
	s_barrier
	v_mfma_f32_16x16x32_bf16 v[116:119], v[188:191], v[88:91], v[116:119]
	v_add_co_u32_e32 v132, vcc, s14, v52
	v_mfma_f32_16x16x32_bf16 v[148:151], v[196:199], v[88:91], v[148:151]
	s_nop 0
	v_addc_co_u32_e32 v133, vcc, 0, v53, vcc
	v_mfma_f32_16x16x32_bf16 v[138:141], v[200:203], v[88:91], v[138:141]
	v_mfma_f32_16x16x32_bf16 v[156:159], v[204:207], v[88:91], v[156:159]
	v_mfma_f32_16x16x32_bf16 v[168:171], v[208:211], v[88:91], v[168:171]
	v_mfma_f32_16x16x32_bf16 v[176:179], v[212:215], v[88:91], v[176:179]
	s_waitcnt lgkmcnt(2)
	v_mfma_f32_16x16x32_bf16 v[48:51], v[216:219], v[88:91], v[220:223]
	v_mfma_f32_16x16x32_bf16 v[88:91], v[216:219], v[100:103], v[96:99]
	ds_read_b128 v[92:95], v145
	s_nop 1
	ds_read_b128 v[96:99], v145 offset:64
	v_mfma_f32_16x16x32_bf16 v[184:187], v[188:191], v[100:103], v[184:187]
	v_mfma_f32_16x16x32_bf16 v[120:123], v[196:199], v[100:103], v[120:123]
	v_mfma_f32_16x16x32_bf16 v[152:155], v[200:203], v[100:103], v[152:155]
	v_mfma_f32_16x16x32_bf16 v[160:163], v[204:207], v[100:103], v[160:163]
	v_mfma_f32_16x16x32_bf16 v[172:175], v[208:211], v[100:103], v[172:175]
	v_mfma_f32_16x16x32_bf16 v[180:183], v[212:215], v[100:103], v[180:183]
	s_waitcnt vmcnt(13) lgkmcnt(1)
	v_mfma_f32_16x16x32_bf16 v[100:103], v[92:95], v[28:31], v[192:195]
	ds_read_b128 v[188:191], v145 offset:2304
	s_nop 1
	ds_read_b128 v[192:195], v145 offset:2368
	s_waitcnt lgkmcnt(1)
	v_mfma_f32_16x16x32_bf16 v[116:119], v[188:191], v[28:31], v[116:119]
	v_mfma_f32_16x16x32_bf16 v[184:187], v[188:191], v[20:23], v[184:187]
	ds_read_b128 v[188:191], v145 offset:4608
	ds_read_b128 v[196:199], v145 offset:4672
	s_waitcnt lgkmcnt(1)
	v_mfma_f32_16x16x32_bf16 v[148:151], v[188:191], v[28:31], v[148:151]
	v_mfma_f32_16x16x32_bf16 v[120:123], v[188:191], v[20:23], v[120:123]
	ds_read_b128 v[188:191], v145 offset:6912
	ds_read_b128 v[200:203], v145 offset:6976
	s_waitcnt lgkmcnt(1)
	v_mfma_f32_16x16x32_bf16 v[138:141], v[188:191], v[28:31], v[138:141]
	v_mfma_f32_16x16x32_bf16 v[152:155], v[188:191], v[20:23], v[152:155]
	ds_read_b128 v[188:191], v145 offset:9216
	ds_read_b128 v[204:207], v145 offset:9280
	s_waitcnt lgkmcnt(1)
; #define LAS __attribute__((address_space(3)))
; #define MFMA16(a, b, c) __builtin_amdgcn_mfma_f32_16x16x32_bf16((a), (b), (c), 0, 0, 0)
; #define S5Y_LOAD(slot, it) do { rb[slot][0] = *(const u32x4*)(Bsrc + (it) * 64); rb[slot][1] = *(const u32x4*)(Bsrc + (size_t)64 * 768 + (it) * 64); \
;         _Pragma("unroll") for (int ks = 0; ks < 2; ++ks) _Pragma("unroll") for (int m = 0; m < 2; ++m) af[slot][ks * 2 + m] = s5_ya(Ab, Xb, m, 2 * (it) + ks); } while (0)
; #define S5Y_PUT(slot, buf) do { *(LAS u32x4*)(bdst + (buf) * BUFB) = rb[slot][0]; *(LAS u32x4*)(bdst + (buf) * BUFB + 64 * ROWB) = rb[slot][1]; } while (0)
; #define S5Y_BAR() do { asm volatile("s_waitcnt lgkmcnt(0)" ::: "memory"); __builtin_amdgcn_s_barrier(); asm volatile("" ::: "memory"); } while (0)
; __device__ __forceinline__ void s5_ygemm(LAS unsigned char* lds, const bf16_t* Z, const bf16_t* W3, const float* E, bf16_t* YG, int unit, int tid) {
;     ...
; #pragma unroll
;     for (int it = 0; it < 12; ++it) {
;         if (it + 4 < 12) S5Y_LOAD((it + 4) % 5, it + 4);
;         const LAS unsigned char* rbuf = brd + (it & 1) * BUFB;
; #pragma unroll
;         for (int ks = 0; ks < 2; ++ks)
; #pragma unroll
;             for (int n = 0; n < 8; ++n) { const bf16x8 bf = *(const LAS bf16x8*)(rbuf + n * 16 * ROWB + ks * 64);
; #pragma unroll
;                 for (int m = 0; m < 2; ++m) acc[m][n] = MFMA16(bf, af[it % 5][ks * 2 + m], acc[m][n]); }
;         if (it + 1 < 12) S5Y_PUT((it + 1) % 5, (it + 1) & 1);
;         S5Y_BAR();
;     }
	v_mfma_f32_16x16x32_bf16 v[156:159], v[188:191], v[28:31], v[156:159]
	v_mfma_f32_16x16x32_bf16 v[160:163], v[188:191], v[20:23], v[160:163]
	ds_read_b128 v[188:191], v145 offset:11520
	ds_read_b128 v[208:211], v145 offset:11584
	s_waitcnt lgkmcnt(1)
	v_mfma_f32_16x16x32_bf16 v[168:171], v[188:191], v[28:31], v[168:171]
	v_mfma_f32_16x16x32_bf16 v[172:175], v[188:191], v[20:23], v[172:175]
	ds_read_b128 v[188:191], v145 offset:13824
	ds_read_b128 v[212:215], v145 offset:13888
	s_waitcnt lgkmcnt(1)
	v_mfma_f32_16x16x32_bf16 v[176:179], v[188:191], v[28:31], v[176:179]
	v_mfma_f32_16x16x32_bf16 v[180:183], v[188:191], v[20:23], v[180:183]
	ds_read_b128 v[188:191], v145 offset:16128
	ds_read_b128 v[216:219], v145 offset:16192
	v_mfma_f32_16x16x32_bf16 v[92:95], v[92:95], v[20:23], v[224:227]
	s_waitcnt lgkmcnt(1)
	v_mfma_f32_16x16x32_bf16 v[220:223], v[188:191], v[28:31], v[48:51]
	v_mfma_f32_16x16x32_bf16 v[188:191], v[188:191], v[20:23], v[88:91]
	v_mfma_f32_16x16x32_bf16 v[100:103], v[96:99], v[76:79], v[100:103]
	v_mfma_f32_16x16x32_bf16 v[96:99], v[96:99], v[72:75], v[92:95]
	s_nop 0
	global_load_dwordx4 v[88:91], v[134:135], off offset:768
	s_nop 0
	global_load_dwordx4 v[92:95], v[136:137], off offset:768
	global_load_dwordx4 v[48:51], v[112:113], off
	global_load_dwordx4 v[52:55], v[132:133], off
	global_load_dwordx4 v[28:31], v[132:133], off offset:1024
	global_load_dwordx4 v[20:23], v[112:113], off offset:1024
	ds_write_b128 v146, v[56:59] offset:18432
	ds_write_b128 v146, v[68:71] offset:27648
	s_waitcnt lgkmcnt(0)
	s_barrier
	v_mfma_f32_16x16x32_bf16 v[116:119], v[192:195], v[76:79], v[116:119]
	v_mfma_f32_16x16x32_bf16 v[184:187], v[192:195], v[72:75], v[184:187]
	v_mfma_f32_16x16x32_bf16 v[148:151], v[196:199], v[76:79], v[148:151]
	v_mfma_f32_16x16x32_bf16 v[120:123], v[196:199], v[72:75], v[120:123]
	v_mfma_f32_16x16x32_bf16 v[138:141], v[200:203], v[76:79], v[138:141]
	v_mfma_f32_16x16x32_bf16 v[152:155], v[200:203], v[72:75], v[152:155]
	v_mfma_f32_16x16x32_bf16 v[156:159], v[204:207], v[76:79], v[156:159]
	v_mfma_f32_16x16x32_bf16 v[160:163], v[204:207], v[72:75], v[160:163]
	v_mfma_f32_16x16x32_bf16 v[168:171], v[208:211], v[76:79], v[168:171]
	v_mfma_f32_16x16x32_bf16 v[172:175], v[208:211], v[72:75], v[172:175]
	v_mfma_f32_16x16x32_bf16 v[176:179], v[212:215], v[76:79], v[176:179]
	v_mfma_f32_16x16x32_bf16 v[180:183], v[212:215], v[72:75], v[180:183]
	s_waitcnt lgkmcnt(2)
	v_mfma_f32_16x16x32_bf16 v[56:59], v[216:219], v[76:79], v[220:223]
	v_mfma_f32_16x16x32_bf16 v[68:71], v[216:219], v[72:75], v[188:191]
	ds_read_b128 v[72:75], v145 offset:18432
	ds_read_b128 v[76:79], v145 offset:18496
	s_waitcnt lgkmcnt(1)
	v_mfma_f32_16x16x32_bf16 v[100:103], v[72:75], v[40:43], v[100:103]
	v_mfma_f32_16x16x32_bf16 v[72:75], v[72:75], v[32:35], v[96:99]
	s_nop 2
	ds_read_b128 v[96:99], v145 offset:20736
	ds_read_b128 v[188:191], v145 offset:20800
	s_waitcnt lgkmcnt(1)
	v_mfma_f32_16x16x32_bf16 v[116:119], v[96:99], v[40:43], v[116:119]
	v_mfma_f32_16x16x32_bf16 v[96:99], v[96:99], v[32:35], v[184:187]
	s_nop 2
	ds_read_b128 v[184:187], v145 offset:23040
	ds_read_b128 v[192:195], v145 offset:23104
	s_waitcnt lgkmcnt(1)
	v_mfma_f32_16x16x32_bf16 v[148:151], v[184:187], v[40:43], v[148:151]
	v_mfma_f32_16x16x32_bf16 v[120:123], v[184:187], v[32:35], v[120:123]
	ds_read_b128 v[184:187], v145 offset:25344
	ds_read_b128 v[196:199], v145 offset:25408
	s_waitcnt lgkmcnt(1)
	v_mfma_f32_16x16x32_bf16 v[138:141], v[184:187], v[40:43], v[138:141]
	v_mfma_f32_16x16x32_bf16 v[152:155], v[184:187], v[32:35], v[152:155]
	ds_read_b128 v[184:187], v145 offset:27648
	ds_read_b128 v[200:203], v145 offset:27712
	s_waitcnt lgkmcnt(1)
	v_mfma_f32_16x16x32_bf16 v[156:159], v[184:187], v[40:43], v[156:159]
	v_mfma_f32_16x16x32_bf16 v[160:163], v[184:187], v[32:35], v[160:163]
	ds_read_b128 v[184:187], v145 offset:29952
	ds_read_b128 v[204:207], v145 offset:30016
	s_waitcnt lgkmcnt(1)
	v_mfma_f32_16x16x32_bf16 v[168:171], v[184:187], v[40:43], v[168:171]
	v_mfma_f32_16x16x32_bf16 v[172:175], v[184:187], v[32:35], v[172:175]
	ds_read_b128 v[184:187], v145 offset:32256
	ds_read_b128 v[208:211], v145 offset:32320
	s_waitcnt lgkmcnt(1)
	v_mfma_f32_16x16x32_bf16 v[176:179], v[184:187], v[40:43], v[176:179]
	v_mfma_f32_16x16x32_bf16 v[180:183], v[184:187], v[32:35], v[180:183]
	ds_read_b128 v[184:187], v145 offset:34560
	ds_read_b128 v[212:215], v145 offset:34624
	s_waitcnt lgkmcnt(1)
	v_mfma_f32_16x16x32_bf16 v[40:43], v[184:187], v[40:43], v[56:59]
	v_mfma_f32_16x16x32_bf16 v[68:71], v[184:187], v[32:35], v[68:71]
	v_mfma_f32_16x16x32_bf16 v[184:187], v[76:79], v[24:27], v[100:103]
	s_waitcnt vmcnt(18)
	v_mfma_f32_16x16x32_bf16 v[72:75], v[76:79], v[16:19], v[72:75]
	v_mfma_f32_16x16x32_bf16 v[116:119], v[188:191], v[24:27], v[116:119]
	v_mfma_f32_16x16x32_bf16 v[188:191], v[188:191], v[16:19], v[96:99]
	s_nop 2
	global_load_dwordx4 v[96:99], v[134:135], off offset:896
	global_load_dwordx4 v[100:103], v[136:137], off offset:896
	global_load_dwordx4 v[56:59], v[132:133], off offset:2048
	v_mfma_f32_16x16x32_bf16 v[148:151], v[192:195], v[24:27], v[148:151]
	v_mfma_f32_16x16x32_bf16 v[138:141], v[196:199], v[24:27], v[138:141]
	v_mfma_f32_16x16x32_bf16 v[156:159], v[200:203], v[24:27], v[156:159]
	v_mfma_f32_16x16x32_bf16 v[168:171], v[204:207], v[24:27], v[168:171]
	v_mfma_f32_16x16x32_bf16 v[176:179], v[208:211], v[24:27], v[176:179]
	s_waitcnt lgkmcnt(0)
	v_mfma_f32_16x16x32_bf16 v[40:43], v[212:215], v[24:27], v[40:43]
	global_load_dwordx4 v[32:35], v[132:133], off offset:3072
	global_load_dwordx4 v[76:79], v[112:113], off offset:2048
	global_load_dwordx4 v[24:27], v[112:113], off offset:3072
	s_waitcnt vmcnt(23)
	ds_write_b128 v146, v[104:107]
	s_waitcnt vmcnt(22)
	ds_write_b128 v146, v[108:111] offset:9216
	s_waitcnt lgkmcnt(0)
	s_barrier
; #define LAS __attribute__((address_space(3)))
; #define MFMA16(a, b, c) __builtin_amdgcn_mfma_f32_16x16x32_bf16((a), (b), (c), 0, 0, 0)
; #define S5Y_LOAD(slot, it) do { rb[slot][0] = *(const u32x4*)(Bsrc + (it) * 64); rb[slot][1] = *(const u32x4*)(Bsrc + (size_t)64 * 768 + (it) * 64); \
;         _Pragma("unroll") for (int ks = 0; ks < 2; ++ks) _Pragma("unroll") for (int m = 0; m < 2; ++m) af[slot][ks * 2 + m] = s5_ya(Ab, Xb, m, 2 * (it) + ks); } while (0)
; #define S5Y_PUT(slot, buf) do { *(LAS u32x4*)(bdst + (buf) * BUFB) = rb[slot][0]; *(LAS u32x4*)(bdst + (buf) * BUFB + 64 * ROWB) = rb[slot][1]; } while (0)
; #define S5Y_BAR() do { asm volatile("s_waitcnt lgkmcnt(0)" ::: "memory"); __builtin_amdgcn_s_barrier(); asm volatile("" ::: "memory"); } while (0)
; __device__ __forceinline__ void s5_ygemm(LAS unsigned char* lds, const bf16_t* Z, const bf16_t* W3, const float* E, bf16_t* YG, int unit, int tid) {
;     ...
; #pragma unroll
;     for (int it = 0; it < 12; ++it) {
;         if (it + 4 < 12) S5Y_LOAD((it + 4) % 5, it + 4);
;         const LAS unsigned char* rbuf = brd + (it & 1) * BUFB;
; #pragma unroll
;         for (int ks = 0; ks < 2; ++ks)
; #pragma unroll
;             for (int n = 0; n < 8; ++n) { const bf16x8 bf = *(const LAS bf16x8*)(rbuf + n * 16 * ROWB + ks * 64);
; #pragma unroll
;                 for (int m = 0; m < 2; ++m) acc[m][n] = MFMA16(bf, af[it % 5][ks * 2 + m], acc[m][n]); }
;         if (it + 1 < 12) S5Y_PUT((it + 1) % 5, (it + 1) & 1);
;         S5Y_BAR();
;     }
	v_mfma_f32_16x16x32_bf16 v[120:123], v[192:195], v[16:19], v[120:123]
	v_or_b32_e32 v132, v114, v143
	v_ashrrev_i32_e32 v133, 31, v132
	v_mfma_f32_16x16x32_bf16 v[152:155], v[196:199], v[16:19], v[152:155]
	v_mfma_f32_16x16x32_bf16 v[160:163], v[200:203], v[16:19], v[160:163]
	v_mfma_f32_16x16x32_bf16 v[172:175], v[204:207], v[16:19], v[172:175]
	v_mfma_f32_16x16x32_bf16 v[180:183], v[208:211], v[16:19], v[180:183]
	v_mfma_f32_16x16x32_bf16 v[16:19], v[212:215], v[16:19], v[68:71]
	s_nop 2
	ds_read_b128 v[68:71], v145
	ds_read_b128 v[104:107], v145 offset:64
	s_waitcnt vmcnt(21) lgkmcnt(1)
	v_mfma_f32_16x16x32_bf16 v[108:111], v[68:71], v[60:63], v[184:187]
	s_waitcnt vmcnt(20)
	v_mfma_f32_16x16x32_bf16 v[68:71], v[68:71], v[64:67], v[72:75]
	s_nop 2
	ds_read_b128 v[72:75], v145 offset:2304
	ds_read_b128 v[184:187], v145 offset:2368
	s_waitcnt lgkmcnt(1)
	v_mfma_f32_16x16x32_bf16 v[116:119], v[72:75], v[60:63], v[116:119]
	v_mfma_f32_16x16x32_bf16 v[72:75], v[72:75], v[64:67], v[188:191]
	s_nop 2
	ds_read_b128 v[188:191], v145 offset:4608
	ds_read_b128 v[192:195], v145 offset:4672
	s_waitcnt lgkmcnt(1)
	v_mfma_f32_16x16x32_bf16 v[148:151], v[188:191], v[60:63], v[148:151]
	v_mfma_f32_16x16x32_bf16 v[120:123], v[188:191], v[64:67], v[120:123]
	ds_read_b128 v[188:191], v145 offset:6912
	ds_read_b128 v[196:199], v145 offset:6976
	s_waitcnt lgkmcnt(1)
	v_mfma_f32_16x16x32_bf16 v[138:141], v[188:191], v[60:63], v[138:141]
	v_mfma_f32_16x16x32_bf16 v[152:155], v[188:191], v[64:67], v[152:155]
	ds_read_b128 v[188:191], v145 offset:9216
	ds_read_b128 v[200:203], v145 offset:9280
	s_waitcnt lgkmcnt(1)
	v_mfma_f32_16x16x32_bf16 v[156:159], v[188:191], v[60:63], v[156:159]
	v_mfma_f32_16x16x32_bf16 v[160:163], v[188:191], v[64:67], v[160:163]
	ds_read_b128 v[188:191], v145 offset:11520
	ds_read_b128 v[204:207], v145 offset:11584
	s_waitcnt lgkmcnt(1)
	v_mfma_f32_16x16x32_bf16 v[168:171], v[188:191], v[60:63], v[168:171]
	v_mfma_f32_16x16x32_bf16 v[172:175], v[188:191], v[64:67], v[172:175]
	ds_read_b128 v[188:191], v145 offset:13824
	ds_read_b128 v[208:211], v145 offset:13888
	s_waitcnt lgkmcnt(1)
	v_mfma_f32_16x16x32_bf16 v[176:179], v[188:191], v[60:63], v[176:179]
	v_mfma_f32_16x16x32_bf16 v[180:183], v[188:191], v[64:67], v[180:183]
	ds_read_b128 v[188:191], v145 offset:16128
	ds_read_b128 v[212:215], v145 offset:16192
	s_waitcnt lgkmcnt(1)
	v_mfma_f32_16x16x32_bf16 v[216:219], v[188:191], v[60:63], v[40:43]
	v_mfma_f32_16x16x32_bf16 v[188:191], v[188:191], v[64:67], v[16:19]
	s_nop 2
	v_lshlrev_b64 v[16:17], 16, v[132:133]
	v_lshl_add_u64 v[16:17], s[0:1], 0, v[16:17]
	v_lshl_add_u64 v[16:17], s[4:5], 2, v[16:17]
	s_waitcnt vmcnt(19)
	v_mfma_f32_16x16x32_bf16 v[116:119], v[184:187], v[8:11], v[116:119]
	s_lshl_b32 s4, s20, 4
	s_ashr_i32 s5, s4, 31
	s_cmpk_lt_i32 s18, 0x300
	s_waitcnt vmcnt(18)
	v_mfma_f32_16x16x32_bf16 v[72:75], v[184:187], v[0:3], v[72:75]
	v_mfma_f32_16x16x32_bf16 v[184:187], v[196:199], v[8:11], v[138:141]
	s_nop 2
	v_lshl_add_u64 v[140:141], v[16:17], 0, v[124:125]
	v_add_co_u32_e32 v138, vcc, s16, v140
	v_mfma_f32_16x16x32_bf16 v[220:223], v[104:107], v[8:11], v[108:111]
	s_nop 0
	v_addc_co_u32_e32 v139, vcc, 0, v141, vcc
	v_mfma_f32_16x16x32_bf16 v[68:71], v[104:107], v[0:3], v[68:71]
	global_load_dwordx4 v[104:107], v[134:135], off offset:1024
	global_load_dwordx4 v[108:111], v[136:137], off offset:1024
	global_load_dwordx4 v[60:63], v[138:139], off
	global_load_dwordx4 v[64:67], v[140:141], off
	global_load_dwordx4 v[40:43], v[140:141], off offset:64
	global_load_dwordx4 v[16:19], v[138:139], off offset:64
	s_waitcnt vmcnt(23)
	ds_write_b128 v146, v[80:83] offset:18432
	s_waitcnt vmcnt(22)
	ds_write_b128 v146, v[84:87] offset:27648
	s_waitcnt lgkmcnt(0)
	s_barrier
	ds_read_b128 v[80:83], v145 offset:18432
	ds_read_b128 v[84:87], v145 offset:18496
	v_mfma_f32_16x16x32_bf16 v[120:123], v[192:195], v[0:3], v[120:123]
	v_mfma_f32_16x16x32_bf16 v[152:155], v[196:199], v[0:3], v[152:155]
	v_mfma_f32_16x16x32_bf16 v[112:115], v[200:203], v[0:3], v[160:163]
	v_mfma_f32_16x16x32_bf16 v[160:163], v[204:207], v[8:11], v[168:171]
	v_mfma_f32_16x16x32_bf16 v[168:171], v[204:207], v[0:3], v[172:175]
	v_mfma_f32_16x16x32_bf16 v[172:175], v[208:211], v[8:11], v[176:179]
	v_mfma_f32_16x16x32_bf16 v[176:179], v[208:211], v[0:3], v[180:183]
	s_waitcnt lgkmcnt(4)
	v_mfma_f32_16x16x32_bf16 v[0:3], v[212:215], v[0:3], v[188:191]
	s_waitcnt vmcnt(20) lgkmcnt(1)
	v_mfma_f32_16x16x32_bf16 v[180:183], v[80:83], v[44:47], v[220:223]
	v_mfma_f32_16x16x32_bf16 v[68:71], v[80:83], v[36:39], v[68:71]
	ds_read_b128 v[80:83], v145 offset:20736
	ds_read_b128 v[188:191], v145 offset:20800
	v_mfma_f32_16x16x32_bf16 v[148:151], v[192:195], v[8:11], v[148:151]
	s_waitcnt lgkmcnt(1)
	v_mfma_f32_16x16x32_bf16 v[116:119], v[80:83], v[44:47], v[116:119]
	v_mfma_f32_16x16x32_bf16 v[72:75], v[80:83], v[36:39], v[72:75]
	ds_read_b128 v[80:83], v145 offset:23040
	ds_read_b128 v[192:195], v145 offset:23104
	s_waitcnt lgkmcnt(1)
	v_mfma_f32_16x16x32_bf16 v[148:151], v[80:83], v[44:47], v[148:151]
	v_mfma_f32_16x16x32_bf16 v[80:83], v[80:83], v[36:39], v[120:123]
	s_nop 2
	ds_read_b128 v[120:123], v145 offset:25344
	ds_read_b128 v[196:199], v145 offset:25408
	v_mfma_f32_16x16x32_bf16 v[156:159], v[200:203], v[8:11], v[156:159]
	s_waitcnt lgkmcnt(1)
	v_mfma_f32_16x16x32_bf16 v[184:187], v[120:123], v[44:47], v[184:187]
	v_mfma_f32_16x16x32_bf16 v[120:123], v[120:123], v[36:39], v[152:155]
	s_nop 2
	ds_read_b128 v[152:155], v145 offset:27648
	ds_read_b128 v[200:203], v145 offset:27712
	s_waitcnt lgkmcnt(1)
; #define LAS __attribute__((address_space(3)))
; #define MFMA16(a, b, c) __builtin_amdgcn_mfma_f32_16x16x32_bf16((a), (b), (c), 0, 0, 0)
; #define S5Y_LOAD(slot, it) do { rb[slot][0] = *(const u32x4*)(Bsrc + (it) * 64); rb[slot][1] = *(const u32x4*)(Bsrc + (size_t)64 * 768 + (it) * 64); \
;         _Pragma("unroll") for (int ks = 0; ks < 2; ++ks) _Pragma("unroll") for (int m = 0; m < 2; ++m) af[slot][ks * 2 + m] = s5_ya(Ab, Xb, m, 2 * (it) + ks); } while (0)
; #define S5Y_PUT(slot, buf) do { *(LAS u32x4*)(bdst + (buf) * BUFB) = rb[slot][0]; *(LAS u32x4*)(bdst + (buf) * BUFB + 64 * ROWB) = rb[slot][1]; } while (0)
; #define S5Y_BAR() do { asm volatile("s_waitcnt lgkmcnt(0)" ::: "memory"); __builtin_amdgcn_s_barrier(); asm volatile("" ::: "memory"); } while (0)
; __device__ __forceinline__ void s5_ygemm(LAS unsigned char* lds, const bf16_t* Z, const bf16_t* W3, const float* E, bf16_t* YG, int unit, int tid) {
;     ...
; #pragma unroll
;     for (int it = 0; it < 12; ++it) {
;         if (it + 4 < 12) S5Y_LOAD((it + 4) % 5, it + 4);
;         const LAS unsigned char* rbuf = brd + (it & 1) * BUFB;
; #pragma unroll
;         for (int ks = 0; ks < 2; ++ks)
; #pragma unroll
;             for (int n = 0; n < 8; ++n) { const bf16x8 bf = *(const LAS bf16x8*)(rbuf + n * 16 * ROWB + ks * 64);
; #pragma unroll
;                 for (int m = 0; m < 2; ++m) acc[m][n] = MFMA16(bf, af[it % 5][ks * 2 + m], acc[m][n]); }
;         if (it + 1 < 12) S5Y_PUT((it + 1) % 5, (it + 1) & 1);
;         S5Y_BAR();
;     }
	v_mfma_f32_16x16x32_bf16 v[156:159], v[152:155], v[44:47], v[156:159]
	v_mfma_f32_16x16x32_bf16 v[112:115], v[152:155], v[36:39], v[112:115]
	ds_read_b128 v[152:155], v145 offset:29952
	ds_read_b128 v[204:207], v145 offset:30016
	s_waitcnt lgkmcnt(1)
	v_mfma_f32_16x16x32_bf16 v[160:163], v[152:155], v[44:47], v[160:163]
	v_mfma_f32_16x16x32_bf16 v[152:155], v[152:155], v[36:39], v[168:171]
	s_nop 2
	ds_read_b128 v[168:171], v145 offset:32256
	ds_read_b128 v[208:211], v145 offset:32320
	v_mfma_f32_16x16x32_bf16 v[8:11], v[212:215], v[8:11], v[216:219]
	s_waitcnt lgkmcnt(1)
	v_mfma_f32_16x16x32_bf16 v[172:175], v[168:171], v[44:47], v[172:175]
	v_mfma_f32_16x16x32_bf16 v[168:171], v[168:171], v[36:39], v[176:179]
	s_nop 2
	ds_read_b128 v[176:179], v145 offset:34560
	ds_read_b128 v[212:215], v145 offset:34624
	s_waitcnt lgkmcnt(1)
	v_mfma_f32_16x16x32_bf16 v[8:11], v[176:179], v[44:47], v[8:11]
	v_mfma_f32_16x16x32_bf16 v[0:3], v[176:179], v[36:39], v[0:3]
	s_waitcnt vmcnt(19)
	v_mfma_f32_16x16x32_bf16 v[176:179], v[84:87], v[12:15], v[180:183]
	s_waitcnt vmcnt(18)
	v_mfma_f32_16x16x32_bf16 v[68:71], v[84:87], v[4:7], v[68:71]
	v_mfma_f32_16x16x32_bf16 v[180:183], v[188:191], v[12:15], v[116:119]
	v_mfma_f32_16x16x32_bf16 v[72:75], v[188:191], v[4:7], v[72:75]
	v_mfma_f32_16x16x32_bf16 v[148:151], v[192:195], v[12:15], v[148:151]
	v_mfma_f32_16x16x32_bf16 v[188:191], v[192:195], v[4:7], v[80:83]
	v_mfma_f32_16x16x32_bf16 v[192:195], v[200:203], v[4:7], v[112:115]
	s_nop 2
	global_load_dwordx4 v[112:115], v[134:135], off offset:1152
	global_load_dwordx4 v[116:119], v[136:137], off offset:1152
	global_load_dwordx4 v[80:83], v[138:139], off offset:128
	global_load_dwordx4 v[84:87], v[140:141], off offset:128
	global_load_dwordx4 v[44:47], v[140:141], off offset:192
	global_load_dwordx4 v[36:39], v[138:139], off offset:192
	s_waitcnt vmcnt(23)
	ds_write_b128 v146, v[88:91]
	s_waitcnt vmcnt(22)
	ds_write_b128 v146, v[92:95] offset:9216
	s_waitcnt lgkmcnt(0)
	s_barrier
	v_mfma_f32_16x16x32_bf16 v[184:187], v[196:199], v[12:15], v[184:187]
	v_mfma_f32_16x16x32_bf16 v[120:123], v[196:199], v[4:7], v[120:123]
	v_mfma_f32_16x16x32_bf16 v[156:159], v[200:203], v[12:15], v[156:159]
	v_mfma_f32_16x16x32_bf16 v[160:163], v[204:207], v[12:15], v[160:163]
	v_mfma_f32_16x16x32_bf16 v[152:155], v[204:207], v[4:7], v[152:155]
	v_mfma_f32_16x16x32_bf16 v[172:175], v[208:211], v[12:15], v[172:175]
	v_mfma_f32_16x16x32_bf16 v[168:171], v[208:211], v[4:7], v[168:171]
	s_waitcnt lgkmcnt(2)
	v_mfma_f32_16x16x32_bf16 v[8:11], v[212:215], v[12:15], v[8:11]
	v_mfma_f32_16x16x32_bf16 v[0:3], v[212:215], v[4:7], v[0:3]
	ds_read_b128 v[4:7], v145
	ds_read_b128 v[12:15], v145 offset:64
	s_waitcnt vmcnt(20) lgkmcnt(1)
	v_mfma_f32_16x16x32_bf16 v[88:91], v[4:7], v[52:55], v[176:179]
	v_mfma_f32_16x16x32_bf16 v[4:7], v[4:7], v[48:51], v[68:71]
	s_nop 2
	ds_read_b128 v[68:71], v145 offset:2304
	ds_read_b128 v[92:95], v145 offset:2368
	s_waitcnt lgkmcnt(1)
	v_mfma_f32_16x16x32_bf16 v[176:179], v[68:71], v[52:55], v[180:183]
	v_mfma_f32_16x16x32_bf16 v[68:71], v[68:71], v[48:51], v[72:75]
	s_nop 2
	ds_read_b128 v[72:75], v145 offset:4608
	ds_read_b128 v[180:183], v145 offset:4672
	s_waitcnt lgkmcnt(1)
	v_mfma_f32_16x16x32_bf16 v[148:151], v[72:75], v[52:55], v[148:151]
	v_mfma_f32_16x16x32_bf16 v[72:75], v[72:75], v[48:51], v[188:191]
	s_nop 2
	ds_read_b128 v[188:191], v145 offset:6912
	ds_read_b128 v[196:199], v145 offset:6976
	s_waitcnt lgkmcnt(1)
	v_mfma_f32_16x16x32_bf16 v[184:187], v[188:191], v[52:55], v[184:187]
	v_mfma_f32_16x16x32_bf16 v[120:123], v[188:191], v[48:51], v[120:123]
	ds_read_b128 v[188:191], v145 offset:9216
	ds_read_b128 v[200:203], v145 offset:9280
	s_waitcnt lgkmcnt(1)
	v_mfma_f32_16x16x32_bf16 v[156:159], v[188:191], v[52:55], v[156:159]
	v_mfma_f32_16x16x32_bf16 v[188:191], v[188:191], v[48:51], v[192:195]
	s_nop 2
	ds_read_b128 v[192:195], v145 offset:11520
	ds_read_b128 v[204:207], v145 offset:11584
	s_waitcnt lgkmcnt(1)
	v_mfma_f32_16x16x32_bf16 v[160:163], v[192:195], v[52:55], v[160:163]
	v_mfma_f32_16x16x32_bf16 v[152:155], v[192:195], v[48:51], v[152:155]
	ds_read_b128 v[192:195], v145 offset:13824
	ds_read_b128 v[208:211], v145 offset:13888
	s_waitcnt lgkmcnt(1)
	v_mfma_f32_16x16x32_bf16 v[172:175], v[192:195], v[52:55], v[172:175]
	v_mfma_f32_16x16x32_bf16 v[168:171], v[192:195], v[48:51], v[168:171]
	ds_read_b128 v[192:195], v145 offset:16128
	ds_read_b128 v[212:215], v145 offset:16192
	s_waitcnt lgkmcnt(1)
	v_mfma_f32_16x16x32_bf16 v[8:11], v[192:195], v[52:55], v[8:11]
	v_mfma_f32_16x16x32_bf16 v[0:3], v[192:195], v[48:51], v[0:3]
	s_waitcnt vmcnt(19)
	v_mfma_f32_16x16x32_bf16 v[88:91], v[12:15], v[28:31], v[88:91]
	s_waitcnt vmcnt(18)
	v_mfma_f32_16x16x32_bf16 v[4:7], v[12:15], v[20:23], v[4:7]
	v_mfma_f32_16x16x32_bf16 v[12:15], v[92:95], v[28:31], v[176:179]
	v_mfma_f32_16x16x32_bf16 v[176:179], v[92:95], v[20:23], v[68:71]
	v_mfma_f32_16x16x32_bf16 v[148:151], v[180:183], v[28:31], v[148:151]
	v_mfma_f32_16x16x32_bf16 v[180:183], v[180:183], v[20:23], v[72:75]
	v_mfma_f32_16x16x32_bf16 v[192:195], v[196:199], v[20:23], v[120:123]
	global_load_dwordx4 v[92:95], v[134:135], off offset:1280
	s_nop 1
	global_load_dwordx4 v[120:123], v[136:137], off offset:1280
	global_load_dwordx4 v[48:51], v[138:139], off offset:512
	global_load_dwordx4 v[52:55], v[140:141], off offset:512
	global_load_dwordx4 v[72:75], v[140:141], off offset:576
	global_load_dwordx4 v[68:71], v[138:139], off offset:576
	s_waitcnt vmcnt(23)
	ds_write_b128 v146, v[96:99] offset:18432
	s_waitcnt vmcnt(22)
	ds_write_b128 v146, v[100:103] offset:27648
	s_waitcnt lgkmcnt(0)
	s_barrier
; #define LAS __attribute__((address_space(3)))
; #define MFMA16(a, b, c) __builtin_amdgcn_mfma_f32_16x16x32_bf16((a), (b), (c), 0, 0, 0)
; #define S5Y_LOAD(slot, it) do { rb[slot][0] = *(const u32x4*)(Bsrc + (it) * 64); rb[slot][1] = *(const u32x4*)(Bsrc + (size_t)64 * 768 + (it) * 64); \
;         _Pragma("unroll") for (int ks = 0; ks < 2; ++ks) _Pragma("unroll") for (int m = 0; m < 2; ++m) af[slot][ks * 2 + m] = s5_ya(Ab, Xb, m, 2 * (it) + ks); } while (0)
; #define S5Y_PUT(slot, buf) do { *(LAS u32x4*)(bdst + (buf) * BUFB) = rb[slot][0]; *(LAS u32x4*)(bdst + (buf) * BUFB + 64 * ROWB) = rb[slot][1]; } while (0)
; #define S5Y_BAR() do { asm volatile("s_waitcnt lgkmcnt(0)" ::: "memory"); __builtin_amdgcn_s_barrier(); asm volatile("" ::: "memory"); } while (0)
; __device__ __forceinline__ void s5_ygemm(LAS unsigned char* lds, const bf16_t* Z, const bf16_t* W3, const float* E, bf16_t* YG, int unit, int tid) {
;     ...
; #pragma unroll
;     for (int it = 0; it < 12; ++it) {
;         if (it + 4 < 12) S5Y_LOAD((it + 4) % 5, it + 4);
;         const LAS unsigned char* rbuf = brd + (it & 1) * BUFB;
; #pragma unroll
;         for (int ks = 0; ks < 2; ++ks)
; #pragma unroll
;             for (int n = 0; n < 8; ++n) { const bf16x8 bf = *(const LAS bf16x8*)(rbuf + n * 16 * ROWB + ks * 64);
; #pragma unroll
;                 for (int m = 0; m < 2; ++m) acc[m][n] = MFMA16(bf, af[it % 5][ks * 2 + m], acc[m][n]); }
;         if (it + 1 < 12) S5Y_PUT((it + 1) % 5, (it + 1) & 1);
;         S5Y_BAR();
;     }
	v_mfma_f32_16x16x32_bf16 v[184:187], v[196:199], v[28:31], v[184:187]
	v_mfma_f32_16x16x32_bf16 v[156:159], v[200:203], v[28:31], v[156:159]
	v_mfma_f32_16x16x32_bf16 v[188:191], v[200:203], v[20:23], v[188:191]
	v_mfma_f32_16x16x32_bf16 v[160:163], v[204:207], v[28:31], v[160:163]
	v_mfma_f32_16x16x32_bf16 v[152:155], v[204:207], v[20:23], v[152:155]
	v_mfma_f32_16x16x32_bf16 v[172:175], v[208:211], v[28:31], v[172:175]
	v_mfma_f32_16x16x32_bf16 v[168:171], v[208:211], v[20:23], v[168:171]
	s_waitcnt lgkmcnt(2)
	v_mfma_f32_16x16x32_bf16 v[8:11], v[212:215], v[28:31], v[8:11]
	v_mfma_f32_16x16x32_bf16 v[0:3], v[212:215], v[20:23], v[0:3]
	ds_read_b128 v[20:23], v145 offset:18432
	ds_read_b128 v[28:31], v145 offset:18496
	s_waitcnt vmcnt(21) lgkmcnt(1)
	v_mfma_f32_16x16x32_bf16 v[88:91], v[20:23], v[56:59], v[88:91]
	s_waitcnt vmcnt(19)
	v_mfma_f32_16x16x32_bf16 v[4:7], v[20:23], v[76:79], v[4:7]
	ds_read_b128 v[20:23], v145 offset:20736
	ds_read_b128 v[96:99], v145 offset:20800
	s_waitcnt lgkmcnt(1)
	v_mfma_f32_16x16x32_bf16 v[12:15], v[20:23], v[56:59], v[12:15]
	v_mfma_f32_16x16x32_bf16 v[20:23], v[20:23], v[76:79], v[176:179]
	ds_read_b128 v[100:103], v145 offset:23040
	s_nop 1
	ds_read_b128 v[176:179], v145 offset:23104
	s_waitcnt lgkmcnt(1)
	v_mfma_f32_16x16x32_bf16 v[148:151], v[100:103], v[56:59], v[148:151]
	v_mfma_f32_16x16x32_bf16 v[100:103], v[100:103], v[76:79], v[180:183]
	s_nop 2
	ds_read_b128 v[180:183], v145 offset:25344
	ds_read_b128 v[196:199], v145 offset:25408
	s_waitcnt lgkmcnt(1)
	v_mfma_f32_16x16x32_bf16 v[184:187], v[180:183], v[56:59], v[184:187]
	v_mfma_f32_16x16x32_bf16 v[180:183], v[180:183], v[76:79], v[192:195]
	s_nop 2
	ds_read_b128 v[192:195], v145 offset:27648
	ds_read_b128 v[200:203], v145 offset:27712
	s_waitcnt lgkmcnt(1)
	v_mfma_f32_16x16x32_bf16 v[156:159], v[192:195], v[56:59], v[156:159]
	v_mfma_f32_16x16x32_bf16 v[188:191], v[192:195], v[76:79], v[188:191]
	ds_read_b128 v[192:195], v145 offset:29952
	ds_read_b128 v[204:207], v145 offset:30016
	s_waitcnt lgkmcnt(1)
	v_mfma_f32_16x16x32_bf16 v[160:163], v[192:195], v[56:59], v[160:163]
	v_mfma_f32_16x16x32_bf16 v[152:155], v[192:195], v[76:79], v[152:155]
	ds_read_b128 v[192:195], v145 offset:32256
	ds_read_b128 v[208:211], v145 offset:32320
	s_waitcnt lgkmcnt(1)
	v_mfma_f32_16x16x32_bf16 v[172:175], v[192:195], v[56:59], v[172:175]
	v_mfma_f32_16x16x32_bf16 v[168:171], v[192:195], v[76:79], v[168:171]
	ds_read_b128 v[192:195], v145 offset:34560
	ds_read_b128 v[212:215], v145 offset:34624
	s_waitcnt lgkmcnt(1)
	v_mfma_f32_16x16x32_bf16 v[8:11], v[192:195], v[56:59], v[8:11]
	v_mfma_f32_16x16x32_bf16 v[56:59], v[192:195], v[76:79], v[0:3]
	v_mfma_f32_16x16x32_bf16 v[192:195], v[28:31], v[32:35], v[88:91]
	s_waitcnt vmcnt(18)
	v_mfma_f32_16x16x32_bf16 v[28:31], v[28:31], v[24:27], v[4:7]
	v_mfma_f32_16x16x32_bf16 v[216:219], v[96:99], v[32:35], v[12:15]
	global_load_dwordx4 v[76:79], v[134:135], off offset:1408
	global_load_dwordx4 v[88:91], v[136:137], off offset:1408
	s_nop 0
	global_load_dwordx4 v[12:15], v[140:141], off offset:640
	v_mfma_f32_16x16x32_bf16 v[20:23], v[96:99], v[24:27], v[20:23]
	v_mfma_f32_16x16x32_bf16 v[96:99], v[176:179], v[32:35], v[148:151]
	v_mfma_f32_16x16x32_bf16 v[148:151], v[196:199], v[32:35], v[184:187]
	v_mfma_f32_16x16x32_bf16 v[156:159], v[200:203], v[32:35], v[156:159]
	v_mfma_f32_16x16x32_bf16 v[160:163], v[204:207], v[32:35], v[160:163]
	v_mfma_f32_16x16x32_bf16 v[172:175], v[208:211], v[32:35], v[172:175]
	s_waitcnt lgkmcnt(0)
	v_mfma_f32_16x16x32_bf16 v[32:35], v[212:215], v[32:35], v[8:11]
	global_load_dwordx4 v[4:7], v[140:141], off offset:704
	s_nop 1
	global_load_dwordx4 v[8:11], v[138:139], off offset:640
	global_load_dwordx4 v[0:3], v[138:139], off offset:704
	s_waitcnt vmcnt(23)
	ds_write_b128 v146, v[104:107]
	s_waitcnt vmcnt(22)
	ds_write_b128 v146, v[108:111] offset:9216
	s_waitcnt lgkmcnt(0)
	s_barrier
	v_mfma_f32_16x16x32_bf16 v[100:103], v[176:179], v[24:27], v[100:103]
	v_mfma_f32_16x16x32_bf16 v[176:179], v[196:199], v[24:27], v[180:183]
	v_mfma_f32_16x16x32_bf16 v[180:183], v[200:203], v[24:27], v[188:191]
	v_mfma_f32_16x16x32_bf16 v[152:155], v[204:207], v[24:27], v[152:155]
	v_mfma_f32_16x16x32_bf16 v[168:171], v[208:211], v[24:27], v[168:171]
	v_mfma_f32_16x16x32_bf16 v[24:27], v[212:215], v[24:27], v[56:59]
	s_nop 2
	ds_read_b128 v[56:59], v145
	ds_read_b128 v[104:107], v145 offset:64
	s_waitcnt vmcnt(20) lgkmcnt(1)
	v_mfma_f32_16x16x32_bf16 v[108:111], v[56:59], v[64:67], v[192:195]
	v_mfma_f32_16x16x32_bf16 v[28:31], v[56:59], v[60:63], v[28:31]
	ds_read_b128 v[56:59], v145 offset:2304
	ds_read_b128 v[134:137], v145 offset:2368
	s_waitcnt lgkmcnt(1)
	v_mfma_f32_16x16x32_bf16 v[138:141], v[56:59], v[64:67], v[216:219]
	v_mfma_f32_16x16x32_bf16 v[20:23], v[56:59], v[60:63], v[20:23]
	ds_read_b128 v[56:59], v145 offset:4608
	ds_read_b128 v[184:187], v145 offset:4672
	s_waitcnt lgkmcnt(1)
	v_mfma_f32_16x16x32_bf16 v[96:99], v[56:59], v[64:67], v[96:99]
	v_mfma_f32_16x16x32_bf16 v[56:59], v[56:59], v[60:63], v[100:103]
	s_nop 2
	ds_read_b128 v[100:103], v145 offset:6912
	ds_read_b128 v[188:191], v145 offset:6976
	s_waitcnt lgkmcnt(1)
	v_mfma_f32_16x16x32_bf16 v[148:151], v[100:103], v[64:67], v[148:151]
	v_mfma_f32_16x16x32_bf16 v[100:103], v[100:103], v[60:63], v[176:179]
	s_nop 2
	ds_read_b128 v[176:179], v145 offset:9216
	ds_read_b128 v[192:195], v145 offset:9280
	s_waitcnt lgkmcnt(1)
	v_mfma_f32_16x16x32_bf16 v[156:159], v[176:179], v[64:67], v[156:159]
	v_mfma_f32_16x16x32_bf16 v[176:179], v[176:179], v[60:63], v[180:183]
	s_nop 2
	ds_read_b128 v[180:183], v145 offset:11520
	ds_read_b128 v[196:199], v145 offset:11584
	s_waitcnt lgkmcnt(1)
	v_mfma_f32_16x16x32_bf16 v[160:163], v[180:183], v[64:67], v[160:163]
	v_mfma_f32_16x16x32_bf16 v[152:155], v[180:183], v[60:63], v[152:155]
	ds_read_b128 v[180:183], v145 offset:13824
	ds_read_b128 v[200:203], v145 offset:13888
	s_waitcnt lgkmcnt(1)
	v_mfma_f32_16x16x32_bf16 v[172:175], v[180:183], v[64:67], v[172:175]
	v_mfma_f32_16x16x32_bf16 v[168:171], v[180:183], v[60:63], v[168:171]
	ds_read_b128 v[180:183], v145 offset:16128
	ds_read_b128 v[204:207], v145 offset:16192
	s_waitcnt vmcnt(17)
	ds_write_b128 v146, v[112:115] offset:18432
	s_waitcnt vmcnt(16)
	ds_write_b128 v146, v[116:119] offset:27648
	s_waitcnt lgkmcnt(0)
	s_waitcnt lgkmcnt(3)
	v_mfma_f32_16x16x32_bf16 v[32:35], v[180:183], v[64:67], v[32:35]
	s_barrier
; #define LAS __attribute__((address_space(3)))
; #define MFMA16(a, b, c) __builtin_amdgcn_mfma_f32_16x16x32_bf16((a), (b), (c), 0, 0, 0)
; #define S5Y_LOAD(slot, it) do { rb[slot][0] = *(const u32x4*)(Bsrc + (it) * 64); rb[slot][1] = *(const u32x4*)(Bsrc + (size_t)64 * 768 + (it) * 64); \
;         _Pragma("unroll") for (int ks = 0; ks < 2; ++ks) _Pragma("unroll") for (int m = 0; m < 2; ++m) af[slot][ks * 2 + m] = s5_ya(Ab, Xb, m, 2 * (it) + ks); } while (0)
; #define S5Y_PUT(slot, buf) do { *(LAS u32x4*)(bdst + (buf) * BUFB) = rb[slot][0]; *(LAS u32x4*)(bdst + (buf) * BUFB + 64 * ROWB) = rb[slot][1]; } while (0)
; #define S5Y_BAR() do { asm volatile("s_waitcnt lgkmcnt(0)" ::: "memory"); __builtin_amdgcn_s_barrier(); asm volatile("" ::: "memory"); } while (0)
; __device__ __forceinline__ void s5_ygemm(LAS unsigned char* lds, const bf16_t* Z, const bf16_t* W3, const float* E, bf16_t* YG, int unit, int tid) {
;     ...
; #pragma unroll
;     for (int it = 0; it < 12; ++it) {
;         if (it + 4 < 12) S5Y_LOAD((it + 4) % 5, it + 4);
;         const LAS unsigned char* rbuf = brd + (it & 1) * BUFB;
; #pragma unroll
;         for (int ks = 0; ks < 2; ++ks)
; #pragma unroll
;             for (int n = 0; n < 8; ++n) { const bf16x8 bf = *(const LAS bf16x8*)(rbuf + n * 16 * ROWB + ks * 64);
; #pragma unroll
;                 for (int m = 0; m < 2; ++m) acc[m][n] = MFMA16(bf, af[it % 5][ks * 2 + m], acc[m][n]); }
;         if (it + 1 < 12) S5Y_PUT((it + 1) % 5, (it + 1) & 1);
;         S5Y_BAR();
;     }
	v_mfma_f32_16x16x32_bf16 v[24:27], v[180:183], v[60:63], v[24:27]
	v_mfma_f32_16x16x32_bf16 v[60:63], v[104:107], v[40:43], v[108:111]
	v_mfma_f32_16x16x32_bf16 v[28:31], v[104:107], v[16:19], v[28:31]
	v_mfma_f32_16x16x32_bf16 v[64:67], v[134:137], v[40:43], v[138:141]
	v_mfma_f32_16x16x32_bf16 v[20:23], v[134:137], v[16:19], v[20:23]
	v_mfma_f32_16x16x32_bf16 v[96:99], v[184:187], v[40:43], v[96:99]
	v_mfma_f32_16x16x32_bf16 v[56:59], v[184:187], v[16:19], v[56:59]
	v_mfma_f32_16x16x32_bf16 v[104:107], v[188:191], v[40:43], v[148:151]
	v_mfma_f32_16x16x32_bf16 v[100:103], v[188:191], v[16:19], v[100:103]
	v_mfma_f32_16x16x32_bf16 v[108:111], v[192:195], v[40:43], v[156:159]
	v_mfma_f32_16x16x32_bf16 v[134:137], v[192:195], v[16:19], v[176:179]
	v_mfma_f32_16x16x32_bf16 v[138:141], v[196:199], v[40:43], v[160:163]
	v_mfma_f32_16x16x32_bf16 v[148:151], v[196:199], v[16:19], v[152:155]
	v_mfma_f32_16x16x32_bf16 v[152:155], v[200:203], v[40:43], v[172:175]
	v_mfma_f32_16x16x32_bf16 v[156:159], v[200:203], v[16:19], v[168:171]
	s_waitcnt lgkmcnt(2)
	v_mfma_f32_16x16x32_bf16 v[32:35], v[204:207], v[40:43], v[32:35]
	v_mfma_f32_16x16x32_bf16 v[16:19], v[204:207], v[16:19], v[24:27]
	s_nop 2
	ds_read_b128 v[24:27], v145 offset:18432
	ds_read_b128 v[40:43], v145 offset:18496
	s_waitcnt vmcnt(14) lgkmcnt(1)
	v_mfma_f32_16x16x32_bf16 v[60:63], v[24:27], v[84:87], v[60:63]
	v_mfma_f32_16x16x32_bf16 v[24:27], v[24:27], v[80:83], v[28:31]
	s_nop 2
	ds_read_b128 v[28:31], v145 offset:20736
	ds_read_b128 v[112:115], v145 offset:20800
	s_waitcnt lgkmcnt(1)
	v_mfma_f32_16x16x32_bf16 v[64:67], v[28:31], v[84:87], v[64:67]
	v_mfma_f32_16x16x32_bf16 v[20:23], v[28:31], v[80:83], v[20:23]
	ds_read_b128 v[28:31], v145 offset:23040
	ds_read_b128 v[116:119], v145 offset:23104
	s_waitcnt lgkmcnt(1)
	v_mfma_f32_16x16x32_bf16 v[96:99], v[28:31], v[84:87], v[96:99]
	v_mfma_f32_16x16x32_bf16 v[28:31], v[28:31], v[80:83], v[56:59]
	s_nop 2
	ds_read_b128 v[56:59], v145 offset:25344
	ds_read_b128 v[160:163], v145 offset:25408
	s_waitcnt lgkmcnt(1)
	v_mfma_f32_16x16x32_bf16 v[104:107], v[56:59], v[84:87], v[104:107]
	v_mfma_f32_16x16x32_bf16 v[56:59], v[56:59], v[80:83], v[100:103]
	s_nop 2
	ds_read_b128 v[100:103], v145 offset:27648
	ds_read_b128 v[168:171], v145 offset:27712
	s_waitcnt lgkmcnt(1)
	v_mfma_f32_16x16x32_bf16 v[108:111], v[100:103], v[84:87], v[108:111]
	v_mfma_f32_16x16x32_bf16 v[100:103], v[100:103], v[80:83], v[134:137]
	s_nop 2
	ds_read_b128 v[134:137], v145 offset:29952
	ds_read_b128 v[172:175], v145 offset:30016
	s_waitcnt lgkmcnt(1)
	v_mfma_f32_16x16x32_bf16 v[138:141], v[134:137], v[84:87], v[138:141]
	v_mfma_f32_16x16x32_bf16 v[134:137], v[134:137], v[80:83], v[148:151]
	s_nop 2
	ds_read_b128 v[148:151], v145 offset:32256
	ds_read_b128 v[176:179], v145 offset:32320
	s_waitcnt lgkmcnt(1)
	v_mfma_f32_16x16x32_bf16 v[152:155], v[148:151], v[84:87], v[152:155]
	v_mfma_f32_16x16x32_bf16 v[148:151], v[148:151], v[80:83], v[156:159]
	s_nop 2
	ds_read_b128 v[156:159], v145 offset:34560
	ds_read_b128 v[180:183], v145 offset:34624
	s_waitcnt vmcnt(11)
	ds_write_b128 v146, v[92:95]
	s_waitcnt vmcnt(10)
	ds_write_b128 v146, v[120:123] offset:9216
	s_waitcnt lgkmcnt(0)
	s_waitcnt lgkmcnt(3)
	v_mfma_f32_16x16x32_bf16 v[32:35], v[156:159], v[84:87], v[32:35]
	s_barrier
	v_mfma_f32_16x16x32_bf16 v[16:19], v[156:159], v[80:83], v[16:19]
	v_mfma_f32_16x16x32_bf16 v[60:63], v[40:43], v[44:47], v[60:63]
	v_mfma_f32_16x16x32_bf16 v[24:27], v[40:43], v[36:39], v[24:27]
	v_mfma_f32_16x16x32_bf16 v[40:43], v[112:115], v[44:47], v[64:67]
	v_mfma_f32_16x16x32_bf16 v[20:23], v[112:115], v[36:39], v[20:23]
	v_mfma_f32_16x16x32_bf16 v[64:67], v[116:119], v[44:47], v[96:99]
	v_mfma_f32_16x16x32_bf16 v[28:31], v[116:119], v[36:39], v[28:31]
	v_mfma_f32_16x16x32_bf16 v[80:83], v[160:163], v[44:47], v[104:107]
	v_mfma_f32_16x16x32_bf16 v[56:59], v[160:163], v[36:39], v[56:59]
	v_mfma_f32_16x16x32_bf16 v[84:87], v[168:171], v[44:47], v[108:111]
	v_mfma_f32_16x16x32_bf16 v[96:99], v[168:171], v[36:39], v[100:103]
	v_mfma_f32_16x16x32_bf16 v[100:103], v[172:175], v[44:47], v[138:141]
	v_mfma_f32_16x16x32_bf16 v[104:107], v[172:175], v[36:39], v[134:137]
	v_mfma_f32_16x16x32_bf16 v[108:111], v[176:179], v[44:47], v[152:155]
	v_mfma_f32_16x16x32_bf16 v[112:115], v[176:179], v[36:39], v[148:151]
	s_waitcnt lgkmcnt(2)
	v_mfma_f32_16x16x32_bf16 v[32:35], v[180:183], v[44:47], v[32:35]
	v_mfma_f32_16x16x32_bf16 v[16:19], v[180:183], v[36:39], v[16:19]
	ds_read_b128 v[36:39], v145
	ds_read_b128 v[44:47], v145 offset:64
	s_waitcnt vmcnt(8) lgkmcnt(1)
	v_mfma_f32_16x16x32_bf16 v[60:63], v[36:39], v[52:55], v[60:63]
	v_mfma_f32_16x16x32_bf16 v[24:27], v[36:39], v[48:51], v[24:27]
	ds_read_b128 v[36:39], v145 offset:2304
	ds_read_b128 v[92:95], v145 offset:2368
	s_waitcnt lgkmcnt(1)
	v_mfma_f32_16x16x32_bf16 v[40:43], v[36:39], v[52:55], v[40:43]
	v_mfma_f32_16x16x32_bf16 v[20:23], v[36:39], v[48:51], v[20:23]
	ds_read_b128 v[36:39], v145 offset:4608
	ds_read_b128 v[116:119], v145 offset:4672
	s_waitcnt lgkmcnt(1)
	v_mfma_f32_16x16x32_bf16 v[120:123], v[36:39], v[52:55], v[64:67]
	v_mfma_f32_16x16x32_bf16 v[28:31], v[36:39], v[48:51], v[28:31]
	ds_read_b128 v[36:39], v145 offset:6912
	ds_read_b128 v[134:137], v145 offset:6976
	s_waitcnt lgkmcnt(1)
	v_mfma_f32_16x16x32_bf16 v[80:83], v[36:39], v[52:55], v[80:83]
	v_mfma_f32_16x16x32_bf16 v[36:39], v[36:39], v[48:51], v[56:59]
	s_nop 2
	ds_read_b128 v[56:59], v145 offset:9216
	ds_read_b128 v[138:141], v145 offset:9280
	s_waitcnt lgkmcnt(1)
	v_mfma_f32_16x16x32_bf16 v[84:87], v[56:59], v[52:55], v[84:87]
	v_mfma_f32_16x16x32_bf16 v[96:99], v[56:59], v[48:51], v[96:99]
	ds_read_b128 v[56:59], v145 offset:11520
	ds_read_b128 v[148:151], v145 offset:11584
	s_waitcnt lgkmcnt(1)
	v_mfma_f32_16x16x32_bf16 v[100:103], v[56:59], v[52:55], v[100:103]
	v_mfma_f32_16x16x32_bf16 v[104:107], v[56:59], v[48:51], v[104:107]
	ds_read_b128 v[56:59], v145 offset:13824
	ds_read_b128 v[152:155], v145 offset:13888
	s_waitcnt lgkmcnt(1)
	v_mfma_f32_16x16x32_bf16 v[108:111], v[56:59], v[52:55], v[108:111]
	v_mfma_f32_16x16x32_bf16 v[112:115], v[56:59], v[48:51], v[112:115]
	ds_read_b128 v[56:59], v145 offset:16128
	ds_read_b128 v[156:159], v145 offset:16192
	s_waitcnt vmcnt(5)
	ds_write_b128 v146, v[76:79] offset:18432
	s_waitcnt vmcnt(4)
	ds_write_b128 v146, v[88:91] offset:27648
	s_waitcnt lgkmcnt(0)
	s_waitcnt lgkmcnt(3)
	v_mfma_f32_16x16x32_bf16 v[168:171], v[56:59], v[48:51], v[16:19]
	s_barrier
; #define LAS __attribute__((address_space(3)))
; #define MFMA16(a, b, c) __builtin_amdgcn_mfma_f32_16x16x32_bf16((a), (b), (c), 0, 0, 0)
; #define S5Y_LOAD(slot, it) do { rb[slot][0] = *(const u32x4*)(Bsrc + (it) * 64); rb[slot][1] = *(const u32x4*)(Bsrc + (size_t)64 * 768 + (it) * 64); \
;         _Pragma("unroll") for (int ks = 0; ks < 2; ++ks) _Pragma("unroll") for (int m = 0; m < 2; ++m) af[slot][ks * 2 + m] = s5_ya(Ab, Xb, m, 2 * (it) + ks); } while (0)
; #define S5Y_PUT(slot, buf) do { *(LAS u32x4*)(bdst + (buf) * BUFB) = rb[slot][0]; *(LAS u32x4*)(bdst + (buf) * BUFB + 64 * ROWB) = rb[slot][1]; } while (0)
; #define S5Y_BAR() do { asm volatile("s_waitcnt lgkmcnt(0)" ::: "memory"); __builtin_amdgcn_s_barrier(); asm volatile("" ::: "memory"); } while (0)
; __device__ __forceinline__ void s5_ygemm(LAS unsigned char* lds, const bf16_t* Z, const bf16_t* W3, const float* E, bf16_t* YG, int unit, int tid) {
;     ...
; #pragma unroll
;     for (int it = 0; it < 12; ++it) {
;         if (it + 4 < 12) S5Y_LOAD((it + 4) % 5, it + 4);
;         const LAS unsigned char* rbuf = brd + (it & 1) * BUFB;
; #pragma unroll
;         for (int ks = 0; ks < 2; ++ks)
; #pragma unroll
;             for (int n = 0; n < 8; ++n) { const bf16x8 bf = *(const LAS bf16x8*)(rbuf + n * 16 * ROWB + ks * 64);
; #pragma unroll
;                 for (int m = 0; m < 2; ++m) acc[m][n] = MFMA16(bf, af[it % 5][ks * 2 + m], acc[m][n]); }
;         if (it + 1 < 12) S5Y_PUT((it + 1) % 5, (it + 1) & 1);
;         S5Y_BAR();
;     }
;     ...
; #pragma unroll
;     for (int m = 0; m < 2; ++m)
; #pragma unroll
;         for (int n = 0; n < 8; ++n)
;         {
;             const int tok = (cbase + m * 16 + fr) * S5T + nq * 8 + n; const f32x4 v = acc[m][n];
	v_mfma_f32_16x16x32_bf16 v[160:163], v[56:59], v[52:55], v[32:35]
	v_mfma_f32_16x16x32_bf16 v[172:175], v[44:47], v[72:75], v[60:63]
	v_mfma_f32_16x16x32_bf16 v[64:67], v[44:47], v[68:71], v[24:27]
	v_mfma_f32_16x16x32_bf16 v[60:63], v[92:95], v[72:75], v[40:43]
	v_mfma_f32_16x16x32_bf16 v[56:59], v[92:95], v[68:71], v[20:23]
	v_mfma_f32_16x16x32_bf16 v[48:51], v[116:119], v[68:71], v[28:31]
	v_mfma_f32_16x16x32_bf16 v[44:47], v[134:137], v[72:75], v[80:83]
	v_mfma_f32_16x16x32_bf16 v[40:43], v[134:137], v[68:71], v[36:39]
	v_mfma_f32_16x16x32_bf16 v[36:39], v[138:141], v[72:75], v[84:87]
	v_mfma_f32_16x16x32_bf16 v[32:35], v[138:141], v[68:71], v[96:99]
	v_lshl_or_b32 v140, v132, 5, s19
	v_or_b32_e32 v164, 2, v140
	v_ashrrev_i32_e32 v141, 31, v140
	v_mfma_f32_16x16x32_bf16 v[24:27], v[148:151], v[68:71], v[104:107]
	v_ashrrev_i32_e32 v165, 31, v164
	v_or_b32_e32 v176, 7, v140
	v_or_b32_e32 v178, 0x200, v140
	v_mfma_f32_16x16x32_bf16 v[16:19], v[152:155], v[68:71], v[112:115]
	v_or_b32_e32 v180, 0x201, v140
	v_or_b32_e32 v182, 0x202, v140
	v_or_b32_e32 v184, 0x203, v140
	s_waitcnt lgkmcnt(2)
	v_mfma_f32_16x16x32_bf16 v[80:83], v[156:159], v[68:71], v[168:171]
	ds_read_b128 v[84:87], v145 offset:18432
	ds_read_b128 v[68:71], v145 offset:18496
	v_or_b32_e32 v186, 0x204, v140
	v_or_b32_e32 v168, 3, v140
	v_mfma_f32_16x16x32_bf16 v[52:55], v[116:119], v[72:75], v[120:123]
	v_or_b32_e32 v170, 4, v140
	v_ashrrev_i32_e32 v169, 31, v168
	v_ashrrev_i32_e32 v171, 31, v170
	v_mfma_f32_16x16x32_bf16 v[28:31], v[148:151], v[72:75], v[100:103]
	v_or_b32_e32 v188, 0x205, v140
	v_or_b32_e32 v190, 0x206, v140
	v_or_b32_e32 v192, 0x207, v140
	v_mfma_f32_16x16x32_bf16 v[20:23], v[152:155], v[72:75], v[108:111]
	v_ashrrev_i32_e32 v177, 31, v176
	v_ashrrev_i32_e32 v179, 31, v178
	v_ashrrev_i32_e32 v181, 31, v180
	v_mfma_f32_16x16x32_bf16 v[76:79], v[156:159], v[72:75], v[160:163]
	v_ashrrev_i32_e32 v183, 31, v182
	v_ashrrev_i32_e32 v185, 31, v184
	v_ashrrev_i32_e32 v187, 31, v186
	s_waitcnt vmcnt(3) lgkmcnt(1)
	v_mfma_f32_16x16x32_bf16 v[72:75], v[84:87], v[12:15], v[172:175]
	v_or_b32_e32 v162, 1, v140
	v_ashrrev_i32_e32 v163, 31, v162
	v_lshl_add_u64 v[160:161], s[4:5], 1, v[128:129]
	s_waitcnt vmcnt(1)
	v_mfma_f32_16x16x32_bf16 v[64:67], v[84:87], v[8:11], v[64:67]
	ds_read_b128 v[84:87], v145 offset:20736
	ds_read_b128 v[88:91], v145 offset:20800
	v_or_b32_e32 v172, 5, v140
	v_or_b32_e32 v174, 6, v140
	s_waitcnt lgkmcnt(1)
	v_mfma_f32_16x16x32_bf16 v[60:63], v[84:87], v[12:15], v[60:63]
	v_ashrrev_i32_e32 v173, 31, v172
	v_ashrrev_i32_e32 v175, 31, v174
	v_ashrrev_i32_e32 v189, 31, v188
	v_mfma_f32_16x16x32_bf16 v[56:59], v[84:87], v[8:11], v[56:59]
	ds_read_b128 v[84:87], v145 offset:23040
	ds_read_b128 v[92:95], v145 offset:23104
	v_ashrrev_i32_e32 v191, 31, v190
	v_ashrrev_i32_e32 v193, 31, v192
	s_waitcnt lgkmcnt(1)
	v_mfma_f32_16x16x32_bf16 v[52:55], v[84:87], v[12:15], v[52:55]
	v_mfma_f32_16x16x32_bf16 v[48:51], v[84:87], v[8:11], v[48:51]
	ds_read_b128 v[84:87], v145 offset:25344
	ds_read_b128 v[96:99], v145 offset:25408
	s_waitcnt lgkmcnt(1)
	v_mfma_f32_16x16x32_bf16 v[100:103], v[84:87], v[12:15], v[44:47]
	v_mfma_f32_16x16x32_bf16 v[84:87], v[84:87], v[8:11], v[40:43]
	s_nop 2
	ds_read_b128 v[40:43], v145 offset:27648
	ds_read_b128 v[104:107], v145 offset:27712
	s_waitcnt lgkmcnt(1)
	v_mfma_f32_16x16x32_bf16 v[108:111], v[40:43], v[12:15], v[36:39]
	s_nop 2
	ds_read_b128 v[36:39], v145 offset:29952
	ds_read_b128 v[112:115], v145 offset:30016
	s_waitcnt lgkmcnt(1)
	v_mfma_f32_16x16x32_bf16 v[116:119], v[36:39], v[8:11], v[24:27]
	s_nop 2
	ds_read_b128 v[24:27], v145 offset:32256
	ds_read_b128 v[120:123], v145 offset:32320
	s_waitcnt lgkmcnt(1)
	v_mfma_f32_16x16x32_bf16 v[136:139], v[24:27], v[8:11], v[16:19]
	s_nop 2
	ds_read_b128 v[16:19], v145 offset:34560
	ds_read_b128 v[148:151], v145 offset:34624
	s_waitcnt lgkmcnt(0)
	s_barrier
	v_mfma_f32_16x16x32_bf16 v[32:35], v[40:43], v[8:11], v[32:35]
	v_mfma_f32_16x16x32_bf16 v[28:31], v[36:39], v[12:15], v[28:31]
	v_mfma_f32_16x16x32_bf16 v[132:135], v[24:27], v[12:15], v[20:23]
	s_waitcnt lgkmcnt(1)
	v_mfma_f32_16x16x32_bf16 v[152:155], v[16:19], v[12:15], v[76:79]
	s_nop 0
	v_lshlrev_b64 v[20:21], 12, v[140:141]
	v_mfma_f32_16x16x32_bf16 v[156:159], v[16:19], v[8:11], v[80:83]
	v_lshlrev_b64 v[76:77], 12, v[174:175]
	v_lshlrev_b64 v[78:79], 12, v[176:177]
	v_lshl_add_u64 v[76:77], v[160:161], 0, v[76:77]
	v_mfma_f32_16x16x32_bf16 v[36:39], v[68:71], v[4:7], v[72:75]
	v_lshlrev_b64 v[80:81], 12, v[178:179]
	v_lshlrev_b64 v[82:83], 12, v[180:181]
	v_lshl_add_u64 v[78:79], v[160:161], 0, v[78:79]
	v_mfma_f32_16x16x32_bf16 v[40:43], v[88:91], v[4:7], v[60:63]
	v_lshlrev_b64 v[74:75], 12, v[172:173]
	v_lshl_add_u64 v[74:75], v[160:161], 0, v[74:75]
	v_lshl_add_u64 v[80:81], v[160:161], 0, v[80:81]
	s_waitcnt vmcnt(0)
; #define LAS __attribute__((address_space(3)))
; __device__ __forceinline__ float gelu_tanh_f(float x) { const float u = 0.7978845608028654f * (x + 0.044715f * x * x * x); return x * sigmoid_f(2.f * u); }
; #define MFMA16(a, b, c) __builtin_amdgcn_mfma_f32_16x16x32_bf16((a), (b), (c), 0, 0, 0)
; #define S5Y_PUT(slot, buf) do { *(LAS u32x4*)(bdst + (buf) * BUFB) = rb[slot][0]; *(LAS u32x4*)(bdst + (buf) * BUFB + 64 * ROWB) = rb[slot][1]; } while (0)
; #define S5Y_BAR() do { asm volatile("s_waitcnt lgkmcnt(0)" ::: "memory"); __builtin_amdgcn_s_barrier(); asm volatile("" ::: "memory"); } while (0)
; __device__ __forceinline__ void s5_ygemm(LAS unsigned char* lds, const bf16_t* Z, const bf16_t* W3, const float* E, bf16_t* YG, int unit, int tid) {
;     ...
;         for (int ks = 0; ks < 2; ++ks)
; #pragma unroll
;             for (int n = 0; n < 8; ++n) { const bf16x8 bf = *(const LAS bf16x8*)(rbuf + n * 16 * ROWB + ks * 64);
; #pragma unroll
;                 for (int m = 0; m < 2; ++m) acc[m][n] = MFMA16(bf, af[it % 5][ks * 2 + m], acc[m][n]); }
;         if (it + 1 < 12) S5Y_PUT((it + 1) % 5, (it + 1) & 1);
;         S5Y_BAR();
;     }
;     ...
; #pragma unroll
;     for (int m = 0; m < 2; ++m)
; #pragma unroll
;         for (int n = 0; n < 8; ++n)
;         {
;             const int tok = (cbase + m * 16 + fr) * S5T + nq * 8 + n; const f32x4 v = acc[m][n];
;             u32x2 w; w.x = pk2(gelu_tanh_f(v[0]), gelu_tanh_f(v[1])); w.y = pk2(gelu_tanh_f(v[2]), gelu_tanh_f(v[3]));
;             *(u32x2*)(YG + (size_t)tok * DM + g * 16 + fq * 4) = w;
	v_mfma_f32_16x16x32_bf16 v[12:15], v[88:91], v[0:3], v[56:59]
	v_lshlrev_b64 v[60:61], 12, v[168:169]
	v_lshlrev_b64 v[62:63], 12, v[170:171]
	v_lshl_add_u64 v[72:73], v[160:161], 0, v[62:63]
	v_lshlrev_b64 v[56:57], 12, v[162:163]
	v_lshlrev_b64 v[58:59], 12, v[164:165]
	v_mfma_f32_16x16x32_bf16 v[8:11], v[68:71], v[0:3], v[64:67]
	v_lshl_add_u64 v[68:69], v[160:161], 0, v[58:59]
	v_lshl_add_u64 v[70:71], v[160:161], 0, v[60:61]
	v_lshlrev_b64 v[88:89], 12, v[186:187]
	v_lshl_add_u64 v[64:65], v[160:161], 0, v[20:21]
	v_mfma_f32_16x16x32_bf16 v[44:47], v[92:95], v[4:7], v[52:55]
	v_lshl_add_u64 v[66:67], v[160:161], 0, v[56:57]
	v_lshlrev_b64 v[90:91], 12, v[188:189]
	v_lshl_add_u64 v[82:83], v[160:161], 0, v[82:83]
	v_mfma_f32_16x16x32_bf16 v[16:19], v[92:95], v[0:3], v[48:51]
	v_lshlrev_b64 v[92:93], 12, v[190:191]
	v_lshlrev_b64 v[94:95], 12, v[192:193]
	v_lshl_add_u64 v[88:89], v[160:161], 0, v[88:89]
	v_mfma_f32_16x16x32_bf16 v[48:51], v[96:99], v[4:7], v[100:103]
	v_lshl_add_u64 v[90:91], v[160:161], 0, v[90:91]
	v_lshl_add_u64 v[92:93], v[160:161], 0, v[92:93]
	v_lshl_add_u64 v[94:95], v[160:161], 0, v[94:95]
	v_mfma_f32_16x16x32_bf16 v[20:23], v[96:99], v[0:3], v[84:87]
	v_mul_f32_e32 v96, 0x3d372713, v36
	v_mul_f32_e32 v97, 0x3d372713, v37
	v_mul_f32_e32 v98, 0x3d372713, v38
	v_mfma_f32_16x16x32_bf16 v[52:55], v[104:107], v[4:7], v[108:111]
	v_lshlrev_b64 v[84:85], 12, v[182:183]
	v_lshlrev_b64 v[86:87], 12, v[184:185]
	v_mul_f32_e32 v99, 0x3d372713, v39
	v_mfma_f32_16x16x32_bf16 v[24:27], v[104:107], v[0:3], v[32:35]
	v_lshl_add_u64 v[84:85], v[160:161], 0, v[84:85]
	v_lshl_add_u64 v[86:87], v[160:161], 0, v[86:87]
	v_mul_f32_e32 v100, 0x3d372713, v40
	v_mfma_f32_16x16x32_bf16 v[56:59], v[112:115], v[4:7], v[28:31]
	v_mul_f32_e32 v101, 0x3d372713, v41
	v_mul_f32_e32 v102, 0x3d372713, v42
	v_mul_f32_e32 v103, 0x3d372713, v43
	v_mfma_f32_16x16x32_bf16 v[28:31], v[112:115], v[0:3], v[116:119]
	v_mul_f32_e32 v104, 0x3d372713, v44
	v_mul_f32_e32 v105, 0x3d372713, v45
	v_mul_f32_e32 v106, 0x3d372713, v46
	v_mfma_f32_16x16x32_bf16 v[60:63], v[120:123], v[4:7], v[132:135]
	v_mul_f32_e32 v107, 0x3d372713, v47
	v_mul_f32_e32 v108, 0x3d372713, v48
	v_mul_f32_e32 v109, 0x3d372713, v49
	v_mfma_f32_16x16x32_bf16 v[32:35], v[120:123], v[0:3], v[136:139]
	v_mul_f32_e32 v110, 0x3d372713, v50
	v_mul_f32_e32 v111, 0x3d372713, v51
	v_mul_f32_e32 v112, 0x3d372713, v52
	s_waitcnt lgkmcnt(0)
	v_mfma_f32_16x16x32_bf16 v[4:7], v[148:151], v[4:7], v[152:155]
	v_mul_f32_e32 v113, 0x3d372713, v53
	v_mul_f32_e32 v114, 0x3d372713, v54
	v_mul_f32_e32 v115, 0x3d372713, v55
	v_mfma_f32_16x16x32_bf16 v[0:3], v[148:151], v[0:3], v[156:159]
	v_mul_f32_e32 v116, 0x3d372713, v56
	v_mul_f32_e32 v117, 0x3d372713, v57
	v_mul_f32_e32 v118, 0x3d372713, v58
	v_mul_f32_e32 v119, 0x3d372713, v59
	v_mul_f32_e32 v120, 0x3d372713, v60
	v_mul_f32_e32 v121, 0x3d372713, v61
	v_mul_f32_e32 v122, 0x3d372713, v62
	v_mul_f32_e32 v123, 0x3d372713, v63
	v_mul_f32_e32 v132, 0x3d372713, v4
	v_mul_f32_e32 v133, 0x3d372713, v5
	v_mul_f32_e32 v134, 0x3d372713, v6
	v_mul_f32_e32 v135, 0x3d372713, v7
	v_mul_f32_e32 v136, 0x3d372713, v8
	v_mul_f32_e32 v137, 0x3d372713, v9
	v_mul_f32_e32 v138, 0x3d372713, v10
	v_mul_f32_e32 v139, 0x3d372713, v11
	v_mul_f32_e32 v140, 0x3d372713, v12
	v_mul_f32_e32 v141, 0x3d372713, v13
	v_mul_f32_e32 v147, 0x3d372713, v14
	v_mul_f32_e32 v148, 0x3d372713, v15
	v_mul_f32_e32 v149, 0x3d372713, v16
	v_mul_f32_e32 v150, 0x3d372713, v17
	v_mul_f32_e32 v151, 0x3d372713, v18
	v_mul_f32_e32 v152, 0x3d372713, v19
	v_mul_f32_e32 v153, 0x3d372713, v20
	v_mul_f32_e32 v154, 0x3d372713, v21
	v_mul_f32_e32 v155, 0x3d372713, v22
	v_mul_f32_e32 v156, 0x3d372713, v23
	v_mul_f32_e32 v157, 0x3d372713, v24
	v_mul_f32_e32 v158, 0x3d372713, v25
	v_mul_f32_e32 v159, 0x3d372713, v26
	v_mul_f32_e32 v160, 0x3d372713, v27
	v_mul_f32_e32 v161, 0x3d372713, v28
	v_mul_f32_e32 v162, 0x3d372713, v29
	v_mul_f32_e32 v163, 0x3d372713, v30
	v_mul_f32_e32 v164, 0x3d372713, v31
	v_mul_f32_e32 v165, 0x3d372713, v32
	v_mul_f32_e32 v168, 0x3d372713, v33
	v_mul_f32_e32 v169, 0x3d372713, v34
	v_mul_f32_e32 v170, 0x3d372713, v35
	v_mul_f32_e32 v171, 0x3d372713, v0
	v_mul_f32_e32 v172, 0x3d372713, v1
	v_mul_f32_e32 v173, 0x3d372713, v2
	v_mul_f32_e32 v174, 0x3d372713, v3
	v_mul_f32_e32 v96, v36, v96
	v_mul_f32_e32 v97, v37, v97
	v_mul_f32_e32 v98, v38, v98
	v_mul_f32_e32 v99, v39, v99
	v_mul_f32_e32 v100, v40, v100
	v_mul_f32_e32 v101, v41, v101
	v_mul_f32_e32 v102, v42, v102
	v_mul_f32_e32 v103, v43, v103
	v_mul_f32_e32 v104, v44, v104
	v_mul_f32_e32 v105, v45, v105
	v_mul_f32_e32 v106, v46, v106
	v_mul_f32_e32 v107, v47, v107
	v_mul_f32_e32 v108, v48, v108
	v_mul_f32_e32 v109, v49, v109
	v_mul_f32_e32 v110, v50, v110
	v_mul_f32_e32 v111, v51, v111
	v_mul_f32_e32 v112, v52, v112
	v_mul_f32_e32 v113, v53, v113
	v_mul_f32_e32 v114, v54, v114
	v_mul_f32_e32 v115, v55, v115
	v_mul_f32_e32 v116, v56, v116
	v_mul_f32_e32 v117, v57, v117
	v_mul_f32_e32 v118, v58, v118
	v_mul_f32_e32 v119, v59, v119
	v_mul_f32_e32 v120, v60, v120
	v_mul_f32_e32 v121, v61, v121
	v_mul_f32_e32 v122, v62, v122
	v_mul_f32_e32 v123, v63, v123
	v_mul_f32_e32 v132, v4, v132
	v_mul_f32_e32 v133, v5, v133
	v_mul_f32_e32 v134, v6, v134
	v_mul_f32_e32 v135, v7, v135
	v_mul_f32_e32 v136, v8, v136
	v_mul_f32_e32 v137, v9, v137
	v_mul_f32_e32 v138, v10, v138
	v_mul_f32_e32 v139, v11, v139
	v_mul_f32_e32 v140, v12, v140
	v_mul_f32_e32 v141, v13, v141
	v_mul_f32_e32 v147, v14, v147
	v_mul_f32_e32 v148, v15, v148
	v_mul_f32_e32 v149, v16, v149
	v_mul_f32_e32 v150, v17, v150
	v_mul_f32_e32 v151, v18, v151
	v_mul_f32_e32 v152, v19, v152
; __device__ __forceinline__ float gelu_tanh_f(float x) { const float u = 0.7978845608028654f * (x + 0.044715f * x * x * x); return x * sigmoid_f(2.f * u); }
; __device__ __forceinline__ float sigmoid_f(float x) { return __builtin_amdgcn_rcpf(1.f + __expf(-x)); }
; __device__ __forceinline__ float silu_f(float x) { return x * sigmoid_f(x); }
; __device__ __forceinline__ float logsigmoid_f(float x) { return fminf(x, 0.f) - log1pf(__expf(-fabsf(x))); }
; __device__ __forceinline__ void s5_ygemm(LAS unsigned char* lds, const bf16_t* Z, const bf16_t* W3, const float* E, bf16_t* YG, int unit, int tid) {
;     ...
;             const int tok = (cbase + m * 16 + fr) * S5T + nq * 8 + n; const f32x4 v = acc[m][n];
;             u32x2 w; w.x = pk2(gelu_tanh_f(v[0]), gelu_tanh_f(v[1])); w.y = pk2(gelu_tanh_f(v[2]), gelu_tanh_f(v[3]));
;             *(u32x2*)(YG + (size_t)tok * DM + g * 16 + fq * 4) = w;
	v_mul_f32_e32 v153, v20, v153
	v_mul_f32_e32 v154, v21, v154
	v_mul_f32_e32 v155, v22, v155
	v_mul_f32_e32 v156, v23, v156
	v_mul_f32_e32 v157, v24, v157
	v_mul_f32_e32 v158, v25, v158
	v_mul_f32_e32 v159, v26, v159
	v_mul_f32_e32 v160, v27, v160
	v_mul_f32_e32 v161, v28, v161
	v_mul_f32_e32 v162, v29, v162
	v_mul_f32_e32 v163, v30, v163
	v_mul_f32_e32 v164, v31, v164
	v_mul_f32_e32 v165, v32, v165
	v_mul_f32_e32 v168, v33, v168
	v_mul_f32_e32 v169, v34, v169
	v_mul_f32_e32 v170, v35, v170
	v_mul_f32_e32 v171, v0, v171
	v_mul_f32_e32 v172, v1, v172
	v_mul_f32_e32 v173, v2, v173
	v_mul_f32_e32 v174, v3, v174
	v_fma_f32 v96, v36, v96, v36
	v_fma_f32 v97, v37, v97, v37
	v_fma_f32 v98, v38, v98, v38
	v_fma_f32 v99, v39, v99, v39
	v_fma_f32 v100, v40, v100, v40
	v_fma_f32 v101, v41, v101, v41
	v_fma_f32 v102, v42, v102, v42
	v_fma_f32 v103, v43, v103, v43
	v_fma_f32 v104, v44, v104, v44
	v_fma_f32 v105, v45, v105, v45
	v_fma_f32 v106, v46, v106, v46
	v_fma_f32 v107, v47, v107, v47
	v_fma_f32 v108, v48, v108, v48
	v_fma_f32 v109, v49, v109, v49
	v_fma_f32 v110, v50, v110, v50
	v_fma_f32 v111, v51, v111, v51
	v_fma_f32 v112, v52, v112, v52
	v_fma_f32 v113, v53, v113, v53
	v_fma_f32 v114, v54, v114, v54
	v_fma_f32 v115, v55, v115, v55
	v_fma_f32 v116, v56, v116, v56
	v_fma_f32 v117, v57, v117, v57
	v_fma_f32 v118, v58, v118, v58
	v_fma_f32 v119, v59, v119, v59
	v_fma_f32 v120, v60, v120, v60
	v_fma_f32 v121, v61, v121, v61
	v_fma_f32 v122, v62, v122, v62
	v_fma_f32 v123, v63, v123, v63
	v_fma_f32 v132, v4, v132, v4
	v_fma_f32 v133, v5, v133, v5
	v_fma_f32 v134, v6, v134, v6
	v_fma_f32 v135, v7, v135, v7
	v_fma_f32 v136, v8, v136, v8
	v_fma_f32 v137, v9, v137, v9
	v_fma_f32 v138, v10, v138, v10
	v_fma_f32 v139, v11, v139, v11
	v_fma_f32 v140, v12, v140, v12
	v_fma_f32 v141, v13, v141, v13
	v_fma_f32 v147, v14, v147, v14
	v_fma_f32 v148, v15, v148, v15
	v_fma_f32 v149, v16, v149, v16
	v_fma_f32 v150, v17, v150, v17
	v_fma_f32 v151, v18, v151, v18
	v_fma_f32 v152, v19, v152, v19
	v_fma_f32 v153, v20, v153, v20
	v_fma_f32 v154, v21, v154, v21
	v_fma_f32 v155, v22, v155, v22
	v_fma_f32 v156, v23, v156, v23
	v_fma_f32 v157, v24, v157, v24
	v_fma_f32 v158, v25, v158, v25
	v_fma_f32 v159, v26, v159, v26
	v_fma_f32 v160, v27, v160, v27
	v_fma_f32 v161, v28, v161, v28
	v_fma_f32 v162, v29, v162, v29
	v_fma_f32 v163, v30, v163, v30
	v_fma_f32 v164, v31, v164, v31
	v_fma_f32 v165, v32, v165, v32
	v_fma_f32 v168, v33, v168, v33
	v_fma_f32 v169, v34, v169, v34
	v_fma_f32 v170, v35, v170, v35
	v_fma_f32 v171, v0, v171, v0
	v_fma_f32 v172, v1, v172, v1
	v_fma_f32 v173, v2, v173, v2
	v_fma_f32 v174, v3, v174, v3
	v_mul_f32_e32 v96, 0x3f4c422a, v96
	v_mul_f32_e32 v97, 0x3f4c422a, v97
	v_mul_f32_e32 v98, 0x3f4c422a, v98
	v_mul_f32_e32 v99, 0x3f4c422a, v99
	v_mul_f32_e32 v100, 0x3f4c422a, v100
	v_mul_f32_e32 v101, 0x3f4c422a, v101
	v_mul_f32_e32 v102, 0x3f4c422a, v102
	v_mul_f32_e32 v103, 0x3f4c422a, v103
	v_mul_f32_e32 v104, 0x3f4c422a, v104
	v_mul_f32_e32 v105, 0x3f4c422a, v105
	v_mul_f32_e32 v106, 0x3f4c422a, v106
	v_mul_f32_e32 v107, 0x3f4c422a, v107
	v_mul_f32_e32 v108, 0x3f4c422a, v108
	v_mul_f32_e32 v109, 0x3f4c422a, v109
	v_mul_f32_e32 v110, 0x3f4c422a, v110
	v_mul_f32_e32 v111, 0x3f4c422a, v111
	v_mul_f32_e32 v112, 0x3f4c422a, v112
	v_mul_f32_e32 v113, 0x3f4c422a, v113
	v_mul_f32_e32 v114, 0x3f4c422a, v114
	v_mul_f32_e32 v115, 0x3f4c422a, v115
	v_mul_f32_e32 v116, 0x3f4c422a, v116
	v_mul_f32_e32 v117, 0x3f4c422a, v117
	v_mul_f32_e32 v118, 0x3f4c422a, v118
	v_mul_f32_e32 v119, 0x3f4c422a, v119
	v_mul_f32_e32 v120, 0x3f4c422a, v120
	v_mul_f32_e32 v121, 0x3f4c422a, v121
	v_mul_f32_e32 v122, 0x3f4c422a, v122
	v_mul_f32_e32 v123, 0x3f4c422a, v123
	v_mul_f32_e32 v132, 0x3f4c422a, v132
	v_mul_f32_e32 v133, 0x3f4c422a, v133
	v_mul_f32_e32 v134, 0x3f4c422a, v134
	v_mul_f32_e32 v135, 0x3f4c422a, v135
	v_mul_f32_e32 v136, 0x3f4c422a, v136
	v_mul_f32_e32 v137, 0x3f4c422a, v137
	v_mul_f32_e32 v138, 0x3f4c422a, v138
	v_mul_f32_e32 v139, 0x3f4c422a, v139
	v_mul_f32_e32 v140, 0x3f4c422a, v140
	v_mul_f32_e32 v141, 0x3f4c422a, v141
	v_mul_f32_e32 v147, 0x3f4c422a, v147
	v_mul_f32_e32 v148, 0x3f4c422a, v148
	v_mul_f32_e32 v149, 0x3f4c422a, v149
	v_mul_f32_e32 v150, 0x3f4c422a, v150
	v_mul_f32_e32 v151, 0x3f4c422a, v151
	v_mul_f32_e32 v152, 0x3f4c422a, v152
	v_mul_f32_e32 v153, 0x3f4c422a, v153
	v_mul_f32_e32 v154, 0x3f4c422a, v154
	v_mul_f32_e32 v155, 0x3f4c422a, v155
	v_mul_f32_e32 v156, 0x3f4c422a, v156
	v_mul_f32_e32 v157, 0x3f4c422a, v157
	v_mul_f32_e32 v158, 0x3f4c422a, v158
	v_mul_f32_e32 v159, 0x3f4c422a, v159
	v_mul_f32_e32 v160, 0x3f4c422a, v160
	v_mul_f32_e32 v161, 0x3f4c422a, v161
	v_mul_f32_e32 v162, 0x3f4c422a, v162
	v_mul_f32_e32 v163, 0x3f4c422a, v163
	v_mul_f32_e32 v164, 0x3f4c422a, v164
	v_mul_f32_e32 v165, 0x3f4c422a, v165
	v_mul_f32_e32 v168, 0x3f4c422a, v168
	v_mul_f32_e32 v169, 0x3f4c422a, v169
	v_mul_f32_e32 v170, 0x3f4c422a, v170
	v_mul_f32_e32 v171, 0x3f4c422a, v171
	v_mul_f32_e32 v172, 0x3f4c422a, v172
	v_mul_f32_e32 v173, 0x3f4c422a, v173
	v_mul_f32_e32 v174, 0x3f4c422a, v174
	v_add_f32_e32 v96, v96, v96
	v_add_f32_e32 v97, v97, v97
	v_add_f32_e32 v98, v98, v98
	v_add_f32_e32 v99, v99, v99
	v_add_f32_e32 v100, v100, v100
	v_add_f32_e32 v101, v101, v101
	v_add_f32_e32 v102, v102, v102
	v_add_f32_e32 v103, v103, v103
	v_add_f32_e32 v104, v104, v104
	v_add_f32_e32 v105, v105, v105
	v_add_f32_e32 v106, v106, v106
	v_add_f32_e32 v107, v107, v107
	v_add_f32_e32 v108, v108, v108
	v_add_f32_e32 v109, v109, v109
	v_add_f32_e32 v110, v110, v110
	v_add_f32_e32 v111, v111, v111
	v_add_f32_e32 v112, v112, v112
	v_add_f32_e32 v113, v113, v113
; __device__ __forceinline__ float gelu_tanh_f(float x) { const float u = 0.7978845608028654f * (x + 0.044715f * x * x * x); return x * sigmoid_f(2.f * u); }
; __device__ __forceinline__ float sigmoid_f(float x) { return __builtin_amdgcn_rcpf(1.f + __expf(-x)); }
; __device__ __forceinline__ float silu_f(float x) { return x * sigmoid_f(x); }
; __device__ __forceinline__ float logsigmoid_f(float x) { return fminf(x, 0.f) - log1pf(__expf(-fabsf(x))); }
; __device__ __forceinline__ void s5_ygemm(LAS unsigned char* lds, const bf16_t* Z, const bf16_t* W3, const float* E, bf16_t* YG, int unit, int tid) {
;     ...
;             const int tok = (cbase + m * 16 + fr) * S5T + nq * 8 + n; const f32x4 v = acc[m][n];
;             u32x2 w; w.x = pk2(gelu_tanh_f(v[0]), gelu_tanh_f(v[1])); w.y = pk2(gelu_tanh_f(v[2]), gelu_tanh_f(v[3]));
;             *(u32x2*)(YG + (size_t)tok * DM + g * 16 + fq * 4) = w;
	v_add_f32_e32 v114, v114, v114
	v_add_f32_e32 v115, v115, v115
	v_add_f32_e32 v116, v116, v116
	v_add_f32_e32 v117, v117, v117
	v_add_f32_e32 v118, v118, v118
	v_add_f32_e32 v119, v119, v119
	v_add_f32_e32 v120, v120, v120
	v_add_f32_e32 v121, v121, v121
	v_add_f32_e32 v122, v122, v122
	v_add_f32_e32 v123, v123, v123
	v_add_f32_e32 v132, v132, v132
	v_add_f32_e32 v133, v133, v133
	v_add_f32_e32 v134, v134, v134
	v_add_f32_e32 v135, v135, v135
	v_add_f32_e32 v136, v136, v136
	v_add_f32_e32 v137, v137, v137
	v_add_f32_e32 v138, v138, v138
	v_add_f32_e32 v139, v139, v139
	v_add_f32_e32 v140, v140, v140
	v_add_f32_e32 v141, v141, v141
	v_add_f32_e32 v147, v147, v147
	v_add_f32_e32 v148, v148, v148
	v_add_f32_e32 v149, v149, v149
	v_add_f32_e32 v150, v150, v150
	v_add_f32_e32 v151, v151, v151
	v_add_f32_e32 v152, v152, v152
	v_add_f32_e32 v153, v153, v153
	v_add_f32_e32 v154, v154, v154
	v_add_f32_e32 v155, v155, v155
	v_add_f32_e32 v156, v156, v156
	v_add_f32_e32 v157, v157, v157
	v_add_f32_e32 v158, v158, v158
	v_add_f32_e32 v159, v159, v159
	v_add_f32_e32 v160, v160, v160
	v_add_f32_e32 v161, v161, v161
	v_add_f32_e32 v162, v162, v162
	v_add_f32_e32 v163, v163, v163
	v_add_f32_e32 v164, v164, v164
	v_add_f32_e32 v165, v165, v165
	v_add_f32_e32 v168, v168, v168
	v_add_f32_e32 v169, v169, v169
	v_add_f32_e32 v170, v170, v170
	v_add_f32_e32 v171, v171, v171
	v_add_f32_e32 v172, v172, v172
	v_add_f32_e32 v173, v173, v173
	v_add_f32_e32 v174, v174, v174
	v_mul_f32_e32 v96, 0xbfb8aa3b, v96
	v_mul_f32_e32 v97, 0xbfb8aa3b, v97
	v_mul_f32_e32 v98, 0xbfb8aa3b, v98
	v_mul_f32_e32 v99, 0xbfb8aa3b, v99
	v_mul_f32_e32 v100, 0xbfb8aa3b, v100
	v_mul_f32_e32 v101, 0xbfb8aa3b, v101
	v_mul_f32_e32 v102, 0xbfb8aa3b, v102
	v_mul_f32_e32 v103, 0xbfb8aa3b, v103
	v_mul_f32_e32 v104, 0xbfb8aa3b, v104
	v_mul_f32_e32 v105, 0xbfb8aa3b, v105
	v_mul_f32_e32 v106, 0xbfb8aa3b, v106
	v_mul_f32_e32 v107, 0xbfb8aa3b, v107
	v_mul_f32_e32 v108, 0xbfb8aa3b, v108
	v_mul_f32_e32 v109, 0xbfb8aa3b, v109
	v_mul_f32_e32 v110, 0xbfb8aa3b, v110
	v_mul_f32_e32 v111, 0xbfb8aa3b, v111
	v_mul_f32_e32 v112, 0xbfb8aa3b, v112
	v_mul_f32_e32 v113, 0xbfb8aa3b, v113
	v_mul_f32_e32 v114, 0xbfb8aa3b, v114
	v_mul_f32_e32 v115, 0xbfb8aa3b, v115
	v_mul_f32_e32 v116, 0xbfb8aa3b, v116
	v_mul_f32_e32 v117, 0xbfb8aa3b, v117
	v_mul_f32_e32 v118, 0xbfb8aa3b, v118
	v_mul_f32_e32 v119, 0xbfb8aa3b, v119
	v_mul_f32_e32 v120, 0xbfb8aa3b, v120
	v_mul_f32_e32 v121, 0xbfb8aa3b, v121
	v_mul_f32_e32 v122, 0xbfb8aa3b, v122
	v_mul_f32_e32 v123, 0xbfb8aa3b, v123
	v_mul_f32_e32 v132, 0xbfb8aa3b, v132
	v_mul_f32_e32 v133, 0xbfb8aa3b, v133
	v_mul_f32_e32 v134, 0xbfb8aa3b, v134
	v_mul_f32_e32 v135, 0xbfb8aa3b, v135
	v_mul_f32_e32 v136, 0xbfb8aa3b, v136
	v_mul_f32_e32 v137, 0xbfb8aa3b, v137
	v_mul_f32_e32 v138, 0xbfb8aa3b, v138
	v_mul_f32_e32 v139, 0xbfb8aa3b, v139
	v_mul_f32_e32 v140, 0xbfb8aa3b, v140
	v_mul_f32_e32 v141, 0xbfb8aa3b, v141
	v_mul_f32_e32 v147, 0xbfb8aa3b, v147
	v_mul_f32_e32 v148, 0xbfb8aa3b, v148
	v_mul_f32_e32 v149, 0xbfb8aa3b, v149
	v_mul_f32_e32 v150, 0xbfb8aa3b, v150
	v_mul_f32_e32 v151, 0xbfb8aa3b, v151
	v_mul_f32_e32 v152, 0xbfb8aa3b, v152
	v_mul_f32_e32 v153, 0xbfb8aa3b, v153
	v_mul_f32_e32 v154, 0xbfb8aa3b, v154
	v_mul_f32_e32 v155, 0xbfb8aa3b, v155
	v_mul_f32_e32 v156, 0xbfb8aa3b, v156
	v_mul_f32_e32 v157, 0xbfb8aa3b, v157
	v_mul_f32_e32 v158, 0xbfb8aa3b, v158
	v_mul_f32_e32 v159, 0xbfb8aa3b, v159
	v_mul_f32_e32 v160, 0xbfb8aa3b, v160
	v_mul_f32_e32 v161, 0xbfb8aa3b, v161
	v_mul_f32_e32 v162, 0xbfb8aa3b, v162
	v_mul_f32_e32 v163, 0xbfb8aa3b, v163
	v_mul_f32_e32 v164, 0xbfb8aa3b, v164
	v_mul_f32_e32 v165, 0xbfb8aa3b, v165
	v_mul_f32_e32 v168, 0xbfb8aa3b, v168
	v_mul_f32_e32 v169, 0xbfb8aa3b, v169
	v_mul_f32_e32 v170, 0xbfb8aa3b, v170
	v_mul_f32_e32 v171, 0xbfb8aa3b, v171
	v_mul_f32_e32 v172, 0xbfb8aa3b, v172
	v_mul_f32_e32 v173, 0xbfb8aa3b, v173
	v_mul_f32_e32 v174, 0xbfb8aa3b, v174
	v_exp_f32_e32 v96, v96
	v_exp_f32_e32 v97, v97
	v_exp_f32_e32 v98, v98
	v_exp_f32_e32 v99, v99
	v_exp_f32_e32 v100, v100
	v_exp_f32_e32 v101, v101
	v_exp_f32_e32 v102, v102
	v_exp_f32_e32 v103, v103
	v_exp_f32_e32 v104, v104
	v_exp_f32_e32 v105, v105
	v_exp_f32_e32 v106, v106
	v_exp_f32_e32 v107, v107
	v_exp_f32_e32 v108, v108
	v_exp_f32_e32 v109, v109
	v_exp_f32_e32 v110, v110
	v_exp_f32_e32 v111, v111
	v_exp_f32_e32 v112, v112
	v_exp_f32_e32 v113, v113
	v_exp_f32_e32 v114, v114
	v_exp_f32_e32 v115, v115
	v_exp_f32_e32 v116, v116
	v_exp_f32_e32 v117, v117
	v_exp_f32_e32 v118, v118
	v_exp_f32_e32 v119, v119
	v_exp_f32_e32 v120, v120
	v_exp_f32_e32 v121, v121
	v_exp_f32_e32 v122, v122
	v_exp_f32_e32 v123, v123
	v_exp_f32_e32 v132, v132
	v_exp_f32_e32 v133, v133
	v_exp_f32_e32 v134, v134
	v_exp_f32_e32 v135, v135
	v_exp_f32_e32 v136, v136
	v_exp_f32_e32 v137, v137
	v_exp_f32_e32 v138, v138
	v_exp_f32_e32 v139, v139
	v_exp_f32_e32 v140, v140
	v_exp_f32_e32 v141, v141
	v_exp_f32_e32 v147, v147
	v_exp_f32_e32 v148, v148
	v_exp_f32_e32 v149, v149
	v_exp_f32_e32 v150, v150
	v_exp_f32_e32 v151, v151
	v_exp_f32_e32 v152, v152
	v_exp_f32_e32 v153, v153
	v_exp_f32_e32 v154, v154
	v_exp_f32_e32 v155, v155
	v_exp_f32_e32 v156, v156
	v_exp_f32_e32 v157, v157
	v_exp_f32_e32 v158, v158
	v_exp_f32_e32 v159, v159
	v_exp_f32_e32 v160, v160
	v_exp_f32_e32 v161, v161
	v_exp_f32_e32 v162, v162
	v_exp_f32_e32 v163, v163
	v_exp_f32_e32 v164, v164
	v_exp_f32_e32 v165, v165
	v_exp_f32_e32 v168, v168
	v_exp_f32_e32 v169, v169
	v_exp_f32_e32 v170, v170
	v_exp_f32_e32 v171, v171
	v_exp_f32_e32 v172, v172
	v_exp_f32_e32 v173, v173
	v_exp_f32_e32 v174, v174
	v_add_f32_e32 v96, 1.0, v96
	v_add_f32_e32 v97, 1.0, v97
	v_add_f32_e32 v98, 1.0, v98
; __device__ __forceinline__ float gelu_tanh_f(float x) { const float u = 0.7978845608028654f * (x + 0.044715f * x * x * x); return x * sigmoid_f(2.f * u); }
; __device__ __forceinline__ float sigmoid_f(float x) { return __builtin_amdgcn_rcpf(1.f + __expf(-x)); }
; __device__ __forceinline__ float silu_f(float x) { return x * sigmoid_f(x); }
; __device__ __forceinline__ float logsigmoid_f(float x) { return fminf(x, 0.f) - log1pf(__expf(-fabsf(x))); }
; __device__ __forceinline__ void s5_ygemm(LAS unsigned char* lds, const bf16_t* Z, const bf16_t* W3, const float* E, bf16_t* YG, int unit, int tid) {
;     ...
;             const int tok = (cbase + m * 16 + fr) * S5T + nq * 8 + n; const f32x4 v = acc[m][n];
;             u32x2 w; w.x = pk2(gelu_tanh_f(v[0]), gelu_tanh_f(v[1])); w.y = pk2(gelu_tanh_f(v[2]), gelu_tanh_f(v[3]));
;             *(u32x2*)(YG + (size_t)tok * DM + g * 16 + fq * 4) = w;
	v_add_f32_e32 v99, 1.0, v99
	v_add_f32_e32 v100, 1.0, v100
	v_add_f32_e32 v101, 1.0, v101
	v_add_f32_e32 v102, 1.0, v102
	v_add_f32_e32 v103, 1.0, v103
	v_add_f32_e32 v104, 1.0, v104
	v_add_f32_e32 v105, 1.0, v105
	v_add_f32_e32 v106, 1.0, v106
	v_add_f32_e32 v107, 1.0, v107
	v_add_f32_e32 v108, 1.0, v108
	v_add_f32_e32 v109, 1.0, v109
	v_add_f32_e32 v110, 1.0, v110
	v_add_f32_e32 v111, 1.0, v111
	v_add_f32_e32 v112, 1.0, v112
	v_add_f32_e32 v113, 1.0, v113
	v_add_f32_e32 v114, 1.0, v114
	v_add_f32_e32 v115, 1.0, v115
	v_add_f32_e32 v116, 1.0, v116
	v_add_f32_e32 v117, 1.0, v117
	v_add_f32_e32 v118, 1.0, v118
	v_add_f32_e32 v119, 1.0, v119
	v_add_f32_e32 v120, 1.0, v120
	v_add_f32_e32 v121, 1.0, v121
	v_add_f32_e32 v122, 1.0, v122
	v_add_f32_e32 v123, 1.0, v123
	v_add_f32_e32 v132, 1.0, v132
	v_add_f32_e32 v133, 1.0, v133
	v_add_f32_e32 v134, 1.0, v134
	v_add_f32_e32 v135, 1.0, v135
	v_add_f32_e32 v136, 1.0, v136
	v_add_f32_e32 v137, 1.0, v137
	v_add_f32_e32 v138, 1.0, v138
	v_add_f32_e32 v139, 1.0, v139
	v_add_f32_e32 v140, 1.0, v140
	v_add_f32_e32 v141, 1.0, v141
	v_add_f32_e32 v147, 1.0, v147
	v_add_f32_e32 v148, 1.0, v148
	v_add_f32_e32 v149, 1.0, v149
	v_add_f32_e32 v150, 1.0, v150
	v_add_f32_e32 v151, 1.0, v151
	v_add_f32_e32 v152, 1.0, v152
	v_add_f32_e32 v153, 1.0, v153
	v_add_f32_e32 v154, 1.0, v154
	v_add_f32_e32 v155, 1.0, v155
	v_add_f32_e32 v156, 1.0, v156
	v_add_f32_e32 v157, 1.0, v157
	v_add_f32_e32 v158, 1.0, v158
	v_add_f32_e32 v159, 1.0, v159
	v_add_f32_e32 v160, 1.0, v160
	v_add_f32_e32 v161, 1.0, v161
	v_add_f32_e32 v162, 1.0, v162
	v_add_f32_e32 v163, 1.0, v163
	v_add_f32_e32 v164, 1.0, v164
	v_add_f32_e32 v165, 1.0, v165
	v_add_f32_e32 v168, 1.0, v168
	v_add_f32_e32 v169, 1.0, v169
	v_add_f32_e32 v170, 1.0, v170
	v_add_f32_e32 v171, 1.0, v171
	v_add_f32_e32 v172, 1.0, v172
	v_add_f32_e32 v173, 1.0, v173
	v_add_f32_e32 v174, 1.0, v174
	v_rcp_f32_e32 v96, v96
	v_rcp_f32_e32 v97, v97
	v_rcp_f32_e32 v98, v98
	v_rcp_f32_e32 v99, v99
	v_rcp_f32_e32 v100, v100
	v_rcp_f32_e32 v101, v101
	v_rcp_f32_e32 v102, v102
	v_rcp_f32_e32 v103, v103
	v_rcp_f32_e32 v104, v104
	v_rcp_f32_e32 v105, v105
	v_rcp_f32_e32 v106, v106
	v_rcp_f32_e32 v107, v107
	v_rcp_f32_e32 v108, v108
	v_rcp_f32_e32 v109, v109
	v_rcp_f32_e32 v110, v110
	v_rcp_f32_e32 v111, v111
	v_rcp_f32_e32 v112, v112
	v_rcp_f32_e32 v113, v113
	v_rcp_f32_e32 v114, v114
	v_rcp_f32_e32 v115, v115
	v_rcp_f32_e32 v116, v116
	v_rcp_f32_e32 v117, v117
	v_rcp_f32_e32 v118, v118
	v_rcp_f32_e32 v119, v119
	v_rcp_f32_e32 v120, v120
	v_rcp_f32_e32 v121, v121
	v_rcp_f32_e32 v122, v122
	v_rcp_f32_e32 v123, v123
	v_rcp_f32_e32 v132, v132
	v_rcp_f32_e32 v133, v133
	v_rcp_f32_e32 v134, v134
	v_rcp_f32_e32 v135, v135
	v_rcp_f32_e32 v136, v136
	v_rcp_f32_e32 v137, v137
	v_rcp_f32_e32 v138, v138
	v_rcp_f32_e32 v139, v139
	v_rcp_f32_e32 v140, v140
	v_rcp_f32_e32 v141, v141
	v_rcp_f32_e32 v147, v147
	v_rcp_f32_e32 v148, v148
	v_rcp_f32_e32 v149, v149
	v_rcp_f32_e32 v150, v150
	v_rcp_f32_e32 v151, v151
	v_rcp_f32_e32 v152, v152
	v_rcp_f32_e32 v153, v153
	v_rcp_f32_e32 v154, v154
	v_rcp_f32_e32 v155, v155
	v_rcp_f32_e32 v156, v156
	v_rcp_f32_e32 v157, v157
	v_rcp_f32_e32 v158, v158
	v_rcp_f32_e32 v159, v159
	v_rcp_f32_e32 v160, v160
	v_rcp_f32_e32 v161, v161
	v_rcp_f32_e32 v162, v162
	v_rcp_f32_e32 v163, v163
	v_rcp_f32_e32 v164, v164
	v_rcp_f32_e32 v165, v165
	v_rcp_f32_e32 v168, v168
	v_rcp_f32_e32 v169, v169
	v_rcp_f32_e32 v170, v170
	v_rcp_f32_e32 v171, v171
	v_rcp_f32_e32 v172, v172
	v_rcp_f32_e32 v173, v173
	v_rcp_f32_e32 v174, v174
	v_mul_f32_e32 v36, v36, v96
	v_mul_f32_e32 v37, v37, v97
	v_mul_f32_e32 v38, v38, v98
	v_mul_f32_e32 v39, v39, v99
	v_mul_f32_e32 v40, v40, v100
	v_mul_f32_e32 v41, v41, v101
	v_mul_f32_e32 v42, v42, v102
	v_mul_f32_e32 v43, v43, v103
	v_mul_f32_e32 v44, v44, v104
	v_mul_f32_e32 v45, v45, v105
	v_mul_f32_e32 v46, v46, v106
	v_mul_f32_e32 v47, v47, v107
	v_mul_f32_e32 v48, v48, v108
	v_mul_f32_e32 v49, v49, v109
	v_mul_f32_e32 v50, v50, v110
	v_mul_f32_e32 v51, v51, v111
	v_mul_f32_e32 v52, v52, v112
	v_mul_f32_e32 v53, v53, v113
	v_mul_f32_e32 v54, v54, v114
	v_mul_f32_e32 v55, v55, v115
	v_mul_f32_e32 v56, v56, v116
	v_mul_f32_e32 v57, v57, v117
	v_mul_f32_e32 v58, v58, v118
	v_mul_f32_e32 v59, v59, v119
	v_mul_f32_e32 v60, v60, v120
	v_mul_f32_e32 v61, v61, v121
	v_mul_f32_e32 v62, v62, v122
	v_mul_f32_e32 v63, v63, v123
	v_mul_f32_e32 v4, v4, v132
	v_mul_f32_e32 v5, v5, v133
	v_mul_f32_e32 v6, v6, v134
	v_mul_f32_e32 v7, v7, v135
	v_mul_f32_e32 v8, v8, v136
	v_mul_f32_e32 v9, v9, v137
	v_mul_f32_e32 v10, v10, v138
	v_mul_f32_e32 v11, v11, v139
	v_mul_f32_e32 v12, v12, v140
; __device__ __forceinline__ float gelu_tanh_f(float x) { const float u = 0.7978845608028654f * (x + 0.044715f * x * x * x); return x * sigmoid_f(2.f * u); }
; __device__ __forceinline__ unsigned pk2(float lo, float hi) {
;     const unsigned ra = __builtin_bit_cast(unsigned, lo) + 0x8000u, rb = __builtin_bit_cast(unsigned, hi) + 0x8000u;
;     return __builtin_amdgcn_perm(rb, ra, 0x07060302u);
; }
; __device__ __forceinline__ void s5_ygemm(LAS unsigned char* lds, const bf16_t* Z, const bf16_t* W3, const float* E, bf16_t* YG, int unit, int tid) {
;     ...
;             const int tok = (cbase + m * 16 + fr) * S5T + nq * 8 + n; const f32x4 v = acc[m][n];
;             u32x2 w; w.x = pk2(gelu_tanh_f(v[0]), gelu_tanh_f(v[1])); w.y = pk2(gelu_tanh_f(v[2]), gelu_tanh_f(v[3]));
;             *(u32x2*)(YG + (size_t)tok * DM + g * 16 + fq * 4) = w;
	v_mul_f32_e32 v13, v13, v141
	v_mul_f32_e32 v14, v14, v147
	v_mul_f32_e32 v15, v15, v148
	v_mul_f32_e32 v16, v16, v149
	v_mul_f32_e32 v17, v17, v150
	v_mul_f32_e32 v18, v18, v151
	v_mul_f32_e32 v19, v19, v152
	v_mul_f32_e32 v20, v20, v153
	v_mul_f32_e32 v21, v21, v154
	v_mul_f32_e32 v22, v22, v155
	v_mul_f32_e32 v23, v23, v156
	v_mul_f32_e32 v24, v24, v157
	v_mul_f32_e32 v25, v25, v158
	v_mul_f32_e32 v26, v26, v159
	v_mul_f32_e32 v27, v27, v160
	v_mul_f32_e32 v28, v28, v161
	v_mul_f32_e32 v29, v29, v162
	v_mul_f32_e32 v30, v30, v163
	v_mul_f32_e32 v31, v31, v164
	v_mul_f32_e32 v32, v32, v165
	v_mul_f32_e32 v33, v33, v168
	v_mul_f32_e32 v34, v34, v169
	v_mul_f32_e32 v35, v35, v170
	v_mul_f32_e32 v0, v0, v171
	v_mul_f32_e32 v1, v1, v172
	v_mul_f32_e32 v2, v2, v173
	v_mul_f32_e32 v3, v3, v174
	v_add_u32_e32 v36, 0x8000, v36
	v_add_u32_e32 v37, 0x8000, v37
	v_add_u32_e32 v38, 0x8000, v38
	v_add_u32_e32 v39, 0x8000, v39
	v_add_u32_e32 v40, 0x8000, v40
	v_add_u32_e32 v41, 0x8000, v41
	v_add_u32_e32 v42, 0x8000, v42
	v_add_u32_e32 v43, 0x8000, v43
	v_add_u32_e32 v44, 0x8000, v44
	v_add_u32_e32 v45, 0x8000, v45
	v_add_u32_e32 v46, 0x8000, v46
	v_add_u32_e32 v47, 0x8000, v47
	v_add_u32_e32 v48, 0x8000, v48
	v_add_u32_e32 v49, 0x8000, v49
	v_add_u32_e32 v50, 0x8000, v50
	v_add_u32_e32 v51, 0x8000, v51
	v_add_u32_e32 v52, 0x8000, v52
	v_add_u32_e32 v53, 0x8000, v53
	v_add_u32_e32 v54, 0x8000, v54
	v_add_u32_e32 v55, 0x8000, v55
	v_add_u32_e32 v56, 0x8000, v56
	v_add_u32_e32 v57, 0x8000, v57
	v_add_u32_e32 v58, 0x8000, v58
	v_add_u32_e32 v59, 0x8000, v59
	v_add_u32_e32 v60, 0x8000, v60
	v_add_u32_e32 v61, 0x8000, v61
	v_add_u32_e32 v62, 0x8000, v62
	v_add_u32_e32 v63, 0x8000, v63
	v_add_u32_e32 v96, 0x8000, v4
	v_add_u32_e32 v97, 0x8000, v5
	v_add_u32_e32 v98, 0x8000, v6
	v_add_u32_e32 v99, 0x8000, v7
	v_add_u32_e32 v100, 0x8000, v8
	v_add_u32_e32 v101, 0x8000, v9
	v_add_u32_e32 v102, 0x8000, v10
	v_add_u32_e32 v103, 0x8000, v11
	v_add_u32_e32 v104, 0x8000, v12
	v_add_u32_e32 v105, 0x8000, v13
	v_add_u32_e32 v106, 0x8000, v14
	v_add_u32_e32 v107, 0x8000, v15
	v_add_u32_e32 v108, 0x8000, v16
	v_add_u32_e32 v109, 0x8000, v17
	v_add_u32_e32 v110, 0x8000, v18
	v_add_u32_e32 v111, 0x8000, v19
	v_add_u32_e32 v112, 0x8000, v20
	v_add_u32_e32 v113, 0x8000, v21
	v_add_u32_e32 v114, 0x8000, v22
	v_add_u32_e32 v23, 0x8000, v23
	v_add_u32_e32 v24, 0x8000, v24
	v_add_u32_e32 v25, 0x8000, v25
	v_add_u32_e32 v26, 0x8000, v26
	v_add_u32_e32 v27, 0x8000, v27
	v_add_u32_e32 v28, 0x8000, v28
	v_add_u32_e32 v29, 0x8000, v29
	v_add_u32_e32 v30, 0x8000, v30
	v_add_u32_e32 v31, 0x8000, v31
	v_add_u32_e32 v32, 0x8000, v32
	v_add_u32_e32 v33, 0x8000, v33
	v_add_u32_e32 v34, 0x8000, v34
	v_add_u32_e32 v35, 0x8000, v35
	v_add_u32_e32 v115, 0x8000, v0
	v_add_u32_e32 v116, 0x8000, v1
	v_add_u32_e32 v117, 0x8000, v2
	v_add_u32_e32 v118, 0x8000, v3
	v_perm_b32 v0, v37, v36, s17
	v_perm_b32 v1, v39, v38, s17
	v_perm_b32 v2, v41, v40, s17
	v_perm_b32 v3, v43, v42, s17
	v_perm_b32 v4, v45, v44, s17
	v_perm_b32 v5, v47, v46, s17
	v_perm_b32 v6, v49, v48, s17
	v_perm_b32 v7, v51, v50, s17
	v_perm_b32 v8, v53, v52, s17
	v_perm_b32 v9, v55, v54, s17
	v_perm_b32 v10, v57, v56, s17
	v_perm_b32 v11, v59, v58, s17
	v_perm_b32 v12, v61, v60, s17
	v_perm_b32 v13, v63, v62, s17
	v_perm_b32 v14, v97, v96, s17
	v_perm_b32 v15, v99, v98, s17
	v_perm_b32 v16, v101, v100, s17
	v_perm_b32 v17, v103, v102, s17
	v_perm_b32 v18, v105, v104, s17
	v_perm_b32 v19, v107, v106, s17
	v_perm_b32 v20, v109, v108, s17
	v_perm_b32 v21, v111, v110, s17
	v_perm_b32 v22, v113, v112, s17
	v_perm_b32 v23, v23, v114, s17
	v_perm_b32 v24, v25, v24, s17
	v_perm_b32 v25, v27, v26, s17
	v_perm_b32 v26, v29, v28, s17
	v_perm_b32 v27, v31, v30, s17
	v_perm_b32 v28, v33, v32, s17
	v_perm_b32 v29, v35, v34, s17
	v_perm_b32 v30, v116, v115, s17
	v_perm_b32 v31, v118, v117, s17
	global_store_dwordx2 v[64:65], v[0:1], off
	global_store_dwordx2 v[66:67], v[2:3], off
	global_store_dwordx2 v[68:69], v[4:5], off
	global_store_dwordx2 v[70:71], v[6:7], off
	global_store_dwordx2 v[72:73], v[8:9], off
	global_store_dwordx2 v[74:75], v[10:11], off
	global_store_dwordx2 v[76:77], v[12:13], off
	global_store_dwordx2 v[78:79], v[14:15], off
	global_store_dwordx2 v[80:81], v[16:17], off
	global_store_dwordx2 v[82:83], v[18:19], off
	global_store_dwordx2 v[84:85], v[20:21], off
	global_store_dwordx2 v[86:87], v[22:23], off
	global_store_dwordx2 v[88:89], v[24:25], off
	global_store_dwordx2 v[90:91], v[26:27], off
	global_store_dwordx2 v[92:93], v[28:29], off
	global_store_dwordx2 v[94:95], v[30:31], off
	s_cbranch_scc1 .LBB0_755
